# P4 output stage: 11 of the 16 gate-row loads issued together up front into unused registers, counted vmcnt per consumer (was: one load + vmcnt(0) per step)
# baseline (speedup 1.0000x reference)
.LBB0_481:
	s_or_b64 exec, exec, s[0:1]
	s_add_u32 s2, s9, s46
	v_and_b32_e32 v146, 16, v146
	s_addc_u32 s4, s8, s47
	s_lshl_b64 s[0:1], s[10:11], 2
	v_cmp_eq_u32_e64 s[36:37], 0, v146
	v_add_u32_e32 v146, 12, v148
	s_add_u32 s0, s2, s0
	v_cndmask_b32_e64 v154, v146, v148, s[36:37]
	v_lshl_add_u32 v146, v0, 2, 0
	s_addc_u32 s1, s4, s1
	v_lshlrev_b32_e32 v18, 2, v148
	v_add_u32_e32 v186, 0x20400, v146
	s_waitcnt lgkmcnt(0)
	s_barrier
	global_load_dwordx4 v[30:33], v18, s[0:1]
	global_load_dwordx4 v[26:29], v18, s[0:1] offset:64
	global_load_dwordx4 v[22:25], v18, s[0:1] offset:128
	s_nop 0
	global_load_dwordx4 v[18:21], v18, s[0:1] offset:192
	ds_read2_b32 v[156:157], v186 offset1:16
	ds_read2_b32 v[158:159], v186 offset0:128 offset1:144
	v_or_b32_e32 v150, s7, v0
	v_mov_b32_e32 v172, 0x3727c5ac
	s_mov_b32 s4, 0xf800000
	s_waitcnt lgkmcnt(1)
	v_add_f32_e32 v0, 0, v156
	s_waitcnt lgkmcnt(0)
	v_add_f32_e32 v0, v0, v158
	v_add_u32_e32 v158, 0x400, v186
	ds_read2_b32 v[160:161], v158 offset1:16
	ds_read2_b32 v[162:163], v158 offset0:128 offset1:144
	v_mov_b32_e32 v173, 0x260
	v_or_b32_e32 v180, s10, v154
	s_addk_i32 s16, 0x3400
	s_waitcnt lgkmcnt(1)
	v_add_f32_e32 v0, v0, v160
	v_add_u32_e32 v160, 0x800, v186
	ds_read2_b32 v[164:165], v160 offset1:16
	s_waitcnt lgkmcnt(1)
	v_add_f32_e32 v0, v0, v162
	ds_read2_b32 v[174:175], v160 offset0:128 offset1:144
	v_add_u32_e32 v162, 0xc00, v186
	ds_read2_b32 v[176:177], v162 offset1:16
	ds_read2_b32 v[178:179], v162 offset0:128 offset1:144
	s_waitcnt lgkmcnt(3)
	v_add_f32_e32 v0, v0, v164
	s_waitcnt lgkmcnt(2)
	v_add_f32_e32 v0, v0, v174
	v_mov_b64_e32 v[152:153], s[44:45]
	s_waitcnt lgkmcnt(1)
	v_add_f32_e32 v0, v0, v176
	s_waitcnt lgkmcnt(0)
	v_add_f32_e32 v0, v0, v178
	v_fmamk_f32 v0, v0, 0x3b000000, v172
	v_cmp_gt_f32_e32 vcc, s4, v0
	v_mul_f32_e32 v146, 0x4f800000, v0
	s_movk_i32 s2, 0x1800
	v_cndmask_b32_e32 v0, v0, v146, vcc
	v_sqrt_f32_e32 v146, v0
	s_lshl_b32 s18, s6, 10
	v_ashrrev_i32_e32 v181, 31, v180
	s_add_i32 s15, s15, s56
	v_add_u32_e32 v147, -1, v146
	v_fma_f32 v148, -v147, v146, v0
	v_cmp_ge_f32_e64 s[0:1], 0, v148
	v_add_u32_e32 v148, 1, v146
	v_mov_b32_e32 v234, 0x3727c5ac
	v_cndmask_b32_e64 v147, v146, v147, s[0:1]
	v_fma_f32 v146, -v148, v146, v0
	v_cmp_lt_f32_e64 s[0:1], 0, v146
	v_mov_b32_e32 v168, 0x260
	s_nop 0
	v_cndmask_b32_e64 v146, v147, v148, s[0:1]
	v_mul_f32_e32 v147, 0x37800000, v146
	v_cndmask_b32_e32 v146, v146, v147, vcc
	v_cmp_class_f32_e32 vcc, v0, v173
	s_nop 1
	v_cndmask_b32_e32 v0, v146, v0, vcc
	v_div_scale_f32 v146, s[0:1], v0, v0, 1.0
	v_rcp_f32_e32 v147, v146
	s_nop 0
	v_fma_f32 v148, -v146, v147, 1.0
	v_fmac_f32_e32 v147, v148, v147
	v_div_scale_f32 v148, vcc, 1.0, v0, 1.0
	v_mul_f32_e32 v149, v148, v147
	v_fma_f32 v151, -v146, v149, v148
	v_fmac_f32_e32 v149, v151, v147
	v_fma_f32 v146, -v146, v149, v148
	v_div_fmas_f32 v146, v146, v147, v149
	v_div_fixup_f32 v156, v146, v0, 1.0
	v_mad_i64_i32 v[148:149], s[0:1], v150, s2, v[152:153]
	v_add_u32_e32 v0, s16, v180
	v_ashrrev_i32_e32 v151, 31, v150
	v_lshl_add_u64 v[182:183], v[148:149], 0, s[18:19]
	v_ashrrev_i32_e32 v148, 8, v0
	v_lshlrev_b64 v[146:147], 9, v[150:151]
	v_ashrrev_i32_e32 v149, 31, v148
	v_mov_b32_e32 v0, s10
	s_movk_i32 s0, 0xdc
	v_lshl_add_u64 v[146:147], s[38:39], 0, v[146:147]
	v_bitop3_b32 v0, v154, s0, v0 bitop3:0xc8
	v_lshlrev_b64 v[154:155], 22, v[148:149]
	v_lshl_add_u64 v[184:185], v[146:147], 0, v[154:155]
	v_lshlrev_b32_e32 v0, 1, v0
	v_lshl_add_u64 v[146:147], v[184:185], 0, v[0:1]
	global_load_dwordx4 v[146:149], v[146:147], off nt
	v_lshl_add_u64 v[232:233], v[184:185], 0, v[0:1]
	s_mov_b32 s78, 0x2000
	s_mov_b32 s79, 0
	global_load_dwordx4 v[188:191], v[232:233], off offset:64 nt
	v_lshl_add_u64 v[232:233], v[232:233], 0, s[78:79]
	global_load_dwordx4 v[192:195], v[232:233], off nt
	global_load_dwordx4 v[196:199], v[232:233], off offset:64 nt
	v_lshl_add_u64 v[232:233], v[232:233], 0, s[78:79]
	global_load_dwordx4 v[200:203], v[232:233], off nt
	global_load_dwordx4 v[204:207], v[232:233], off offset:64 nt
	v_lshl_add_u64 v[232:233], v[232:233], 0, s[78:79]
	global_load_dwordx4 v[208:211], v[232:233], off nt
	global_load_dwordx4 v[212:215], v[232:233], off offset:64 nt
	v_lshl_add_u64 v[232:233], v[232:233], 0, s[78:79]
	global_load_dwordx4 v[216:219], v[232:233], off nt
	global_load_dwordx4 v[220:223], v[232:233], off offset:64 nt
	v_lshl_add_u64 v[232:233], v[232:233], 0, s[78:79]
	global_load_dwordx4 v[224:227], v[232:233], off nt
	global_load_dwordx4 v[228:231], v[232:233], off offset:64 nt
	v_pk_mul_f32 v[140:141], v[140:141], v[156:157] op_sel_hi:[1,0]
	v_pk_mul_f32 v[144:145], v[144:145], v[156:157] op_sel_hi:[1,0]
	s_waitcnt vmcnt(15)
	v_pk_mul_f32 v[140:141], v[32:33], v[140:141]
	s_waitcnt vmcnt(14)
	v_pk_mul_f32 v[144:145], v[28:29], v[144:145]
	v_pk_mul_f32 v[138:139], v[138:139], v[156:157] op_sel_hi:[1,0]
	v_cndmask_b32_e64 v166, v140, v144, s[36:37]
	ds_swizzle_b32 v166, v166 offset:swizzle(SWAP,16)
	v_cndmask_b32_e64 v167, v141, v145, s[36:37]
	ds_swizzle_b32 v167, v167 offset:swizzle(SWAP,16)
	v_pk_mul_f32 v[142:143], v[142:143], v[156:157] op_sel_hi:[1,0]
	v_pk_mul_f32 v[138:139], v[30:31], v[138:139]
	s_waitcnt lgkmcnt(1)
	v_cndmask_b32_e64 v140, v166, v140, s[36:37]
	v_cndmask_b32_e64 v166, v144, v166, s[36:37]
	s_waitcnt lgkmcnt(0)
	v_cndmask_b32_e64 v141, v167, v141, s[36:37]
	v_cndmask_b32_e64 v167, v145, v167, s[36:37]
	v_pk_mul_f32 v[142:143], v[26:27], v[142:143]
	s_movk_i32 s0, 0xfc
	v_cndmask_b32_e64 v151, v138, v142, s[36:37]
	v_cndmask_b32_e64 v164, v139, v143, s[36:37]
	ds_swizzle_b32 v151, v151 offset:swizzle(SWAP,16)
	ds_swizzle_b32 v164, v164 offset:swizzle(SWAP,16)
	v_pk_mul_f32 v[130:131], v[130:131], v[156:157] op_sel_hi:[1,0]
	v_pk_mul_f32 v[134:135], v[134:135], v[156:157] op_sel_hi:[1,0]
	s_waitcnt vmcnt(13)
	v_pk_mul_f32 v[130:131], v[22:23], v[130:131]
	s_waitcnt lgkmcnt(1)
	v_cndmask_b32_e64 v138, v151, v138, s[36:37]
	s_waitcnt lgkmcnt(0)
	v_cndmask_b32_e64 v139, v164, v139, s[36:37]
	v_cndmask_b32_e64 v143, v143, v164, s[36:37]
	v_cndmask_b32_e64 v142, v142, v151, s[36:37]
	s_waitcnt vmcnt(12)
	v_pk_mul_f32 v[134:135], v[18:19], v[134:135]
	v_pk_mul_f32 v[132:133], v[132:133], v[156:157] op_sel_hi:[1,0]
	v_pk_mul_f32 v[136:137], v[136:137], v[156:157] op_sel_hi:[1,0]
	v_pk_mul_f32 v[132:133], v[24:25], v[132:133]
	v_pk_mul_f32 v[136:137], v[20:21], v[136:137]
	s_waitcnt vmcnt(11)
	v_lshlrev_b32_e32 v144, 16, v146
	v_and_b32_e32 v145, 0xffff0000, v146
	v_mul_f32_e32 v146, 0xbfb8aa3b, v144
	v_exp_f32_e32 v146, v146
	v_cndmask_b32_e64 v151, v132, v136, s[36:37]
	v_cndmask_b32_e64 v156, v133, v137, s[36:37]
	ds_swizzle_b32 v151, v151 offset:swizzle(SWAP,16)
	v_add_f32_e32 v146, 1.0, v146
	v_rcp_f32_e32 v170, v146
	v_mul_f32_e32 v146, 0xbfb8aa3b, v145
	v_exp_f32_e32 v146, v146
	ds_swizzle_b32 v156, v156 offset:swizzle(SWAP,16)
	s_waitcnt lgkmcnt(1)
	v_cndmask_b32_e64 v132, v151, v132, s[36:37]
	v_cndmask_b32_e64 v136, v136, v151, s[36:37]
	v_add_f32_e32 v146, 1.0, v146
	v_rcp_f32_e32 v171, v146
	s_waitcnt lgkmcnt(0)
	v_cndmask_b32_e64 v133, v156, v133, s[36:37]
	v_cndmask_b32_e64 v137, v137, v156, s[36:37]
	v_pk_mul_f32 v[144:145], v[170:171], v[144:145]
	s_nop 0
	v_pk_mul_f32 v[138:139], v[144:145], v[138:139]
	s_nop 0
	v_cvt_pk_bf16_f32 v144, v138, v139
	v_lshlrev_b32_e32 v138, 16, v147
	v_mul_f32_e32 v145, 0xbfb8aa3b, v138
	v_exp_f32_e32 v145, v145
	v_and_b32_e32 v139, 0xffff0000, v147
	v_add_f32_e32 v145, 1.0, v145
	v_rcp_f32_e32 v146, v145
	v_mul_f32_e32 v145, 0xbfb8aa3b, v139
	v_exp_f32_e32 v145, v145
	s_nop 0
	v_add_f32_e32 v145, 1.0, v145
	v_rcp_f32_e32 v147, v145
	s_nop 0
	v_pk_mul_f32 v[138:139], v[146:147], v[138:139]
	s_nop 0
	v_pk_mul_f32 v[138:139], v[138:139], v[140:141]
	s_nop 0
	v_cvt_pk_bf16_f32 v145, v138, v139
	v_lshlrev_b32_e32 v138, 16, v148
	v_and_b32_e32 v139, 0xffff0000, v148
	v_mul_f32_e32 v140, 0xbfb8aa3b, v138
	v_mul_f32_e32 v141, 0xbfb8aa3b, v139
	v_exp_f32_e32 v140, v140
	v_exp_f32_e32 v141, v141
	v_cndmask_b32_e64 v148, v130, v134, s[36:37]
	ds_swizzle_b32 v148, v148 offset:swizzle(SWAP,16)
	v_add_f32_e32 v140, 1.0, v140
	v_add_f32_e32 v141, 1.0, v141
	v_rcp_f32_e32 v140, v140
	v_rcp_f32_e32 v141, v141
	s_waitcnt lgkmcnt(0)
	v_cndmask_b32_e64 v130, v148, v130, s[36:37]
	v_cndmask_b32_e64 v134, v134, v148, s[36:37]
	v_pk_mul_f32 v[138:139], v[140:141], v[138:139]
	s_nop 0
	v_pk_mul_f32 v[138:139], v[138:139], v[142:143]
	s_nop 0
	v_cvt_pk_bf16_f32 v146, v138, v139
	v_lshlrev_b32_e32 v138, 16, v149
	v_and_b32_e32 v139, 0xffff0000, v149
	v_mul_f32_e32 v140, 0xbfb8aa3b, v138
	v_mul_f32_e32 v141, 0xbfb8aa3b, v139
	v_exp_f32_e32 v140, v140
	v_exp_f32_e32 v141, v141
	v_cndmask_b32_e64 v149, v131, v135, s[36:37]
	ds_swizzle_b32 v149, v149 offset:swizzle(SWAP,16)
	v_add_f32_e32 v140, 1.0, v140
	v_add_f32_e32 v141, 1.0, v141
	v_rcp_f32_e32 v140, v140
	v_rcp_f32_e32 v141, v141
	s_waitcnt lgkmcnt(0)
	v_cndmask_b32_e64 v131, v149, v131, s[36:37]
	v_cndmask_b32_e64 v135, v135, v149, s[36:37]
	v_pk_mul_f32 v[138:139], v[140:141], v[138:139]
	s_nop 0
	v_pk_mul_f32 v[138:139], v[138:139], v[166:167]
	v_bitop3_b32 v140, v180, s0, 32 bitop3:0xc8
	v_cvt_pk_bf16_f32 v147, v138, v139
	v_lshlrev_b64 v[138:139], 1, v[180:181]
	v_lshl_add_u64 v[142:143], v[182:183], 0, v[138:139]
	v_lshlrev_b32_e32 v140, 1, v140
	v_mov_b32_e32 v141, v1
	global_store_dwordx4 v[142:143], v[144:147], off offset:2048
	s_nop 1
	s_waitcnt vmcnt(11)
	v_lshlrev_b32_e32 v148, 16, v188
	v_and_b32_e32 v149, 0xffff0000, v188
	v_mul_f32_e32 v144, 0xbfb8aa3b, v148
	v_exp_f32_e32 v144, v144
	s_nop 0
	v_add_f32_e32 v144, 1.0, v144
	v_rcp_f32_e32 v166, v144
	v_mul_f32_e32 v144, 0xbfb8aa3b, v149
	v_exp_f32_e32 v144, v144
	s_nop 0
	v_add_f32_e32 v144, 1.0, v144
	v_rcp_f32_e32 v167, v144
	v_lshlrev_b32_e32 v144, 16, v189
	v_and_b32_e32 v145, 0xffff0000, v189
	v_pk_mul_f32 v[148:149], v[166:167], v[148:149]
	s_nop 0
	v_pk_mul_f32 v[130:131], v[148:149], v[130:131]
	s_nop 0
	v_cvt_pk_bf16_f32 v130, v130, v131
	v_mul_f32_e32 v131, 0xbfb8aa3b, v144
	v_exp_f32_e32 v131, v131
	s_nop 0
	v_add_f32_e32 v131, 1.0, v131
	v_rcp_f32_e32 v148, v131
	v_mul_f32_e32 v131, 0xbfb8aa3b, v145
	v_exp_f32_e32 v131, v131
	s_nop 0
	v_add_f32_e32 v131, 1.0, v131
	v_rcp_f32_e32 v149, v131
	s_nop 0
	v_pk_mul_f32 v[144:145], v[148:149], v[144:145]
	s_nop 0
	v_pk_mul_f32 v[132:133], v[144:145], v[132:133]
	s_nop 0
	v_cvt_pk_bf16_f32 v131, v132, v133
	v_lshlrev_b32_e32 v132, 16, v190
	v_and_b32_e32 v133, 0xffff0000, v190
	v_mul_f32_e32 v144, 0xbfb8aa3b, v132
	v_mul_f32_e32 v145, 0xbfb8aa3b, v133
	v_exp_f32_e32 v144, v144
	v_exp_f32_e32 v145, v145
	v_add_f32_e32 v144, 1.0, v144
	v_add_f32_e32 v145, 1.0, v145
	v_rcp_f32_e32 v144, v144
	v_rcp_f32_e32 v145, v145
	s_nop 0
	v_pk_mul_f32 v[132:133], v[144:145], v[132:133]
	s_nop 0
	v_pk_mul_f32 v[132:133], v[132:133], v[134:135]
	v_lshlrev_b32_e32 v134, 16, v191
	v_cvt_pk_bf16_f32 v132, v132, v133
	v_mul_f32_e32 v133, 0xbfb8aa3b, v134
	v_exp_f32_e32 v133, v133
	v_and_b32_e32 v135, 0xffff0000, v191
	v_add_f32_e32 v133, 1.0, v133
	v_rcp_f32_e32 v144, v133
	v_mul_f32_e32 v133, 0xbfb8aa3b, v135
	v_exp_f32_e32 v133, v133
	s_nop 0
	v_add_f32_e32 v133, 1.0, v133
	v_rcp_f32_e32 v145, v133
	s_nop 0
	v_pk_mul_f32 v[134:135], v[144:145], v[134:135]
	s_nop 0
	v_pk_mul_f32 v[134:135], v[134:135], v[136:137]
	s_nop 0
	v_cvt_pk_bf16_f32 v133, v134, v135
	global_store_dwordx4 v[142:143], v[130:133], off offset:2112
	s_nop 1
	v_add_f32_e32 v130, 0, v157
	v_add_f32_e32 v130, v130, v159
	v_add_f32_e32 v130, v130, v161
	v_add_f32_e32 v130, v130, v163
	v_add_f32_e32 v130, v130, v165
	v_add_f32_e32 v130, v130, v175
	v_add_f32_e32 v130, v130, v177
	v_add_f32_e32 v130, v130, v179
	v_fmamk_f32 v130, v130, 0x3b000000, v172
	v_cmp_gt_f32_e32 vcc, s4, v130
	v_mul_f32_e32 v131, 0x4f800000, v130
	s_nop 0
	v_cndmask_b32_e32 v130, v130, v131, vcc
	v_sqrt_f32_e32 v131, v130
	s_nop 0
	v_add_u32_e32 v132, -1, v131
	v_fma_f32 v133, -v132, v131, v130
	v_cmp_ge_f32_e64 s[0:1], 0, v133
	v_add_u32_e32 v133, 1, v131
	s_nop 0
	v_cndmask_b32_e64 v132, v131, v132, s[0:1]
	v_fma_f32 v131, -v133, v131, v130
	v_cmp_lt_f32_e64 s[0:1], 0, v131
	s_nop 1
	v_cndmask_b32_e64 v131, v132, v133, s[0:1]
	v_mul_f32_e32 v132, 0x37800000, v131
	v_cndmask_b32_e32 v131, v131, v132, vcc
	v_cmp_class_f32_e32 vcc, v130, v173
	s_nop 1
	v_cndmask_b32_e32 v130, v131, v130, vcc
	v_div_scale_f32 v131, s[0:1], v130, v130, 1.0
	v_rcp_f32_e32 v132, v131
	s_nop 0
	v_fma_f32 v133, -v131, v132, 1.0
	v_fmac_f32_e32 v132, v133, v132
	v_div_scale_f32 v133, vcc, 1.0, v130, 1.0
	v_mul_f32_e32 v134, v133, v132
	v_fma_f32 v135, -v131, v134, v133
	v_fmac_f32_e32 v134, v135, v132
	v_fma_f32 v131, -v131, v134, v133
	v_div_fmas_f32 v131, v131, v132, v134
	v_div_fixup_f32 v134, v131, v130, 1.0
	v_or_b32_e32 v130, 16, v150
	v_ashrrev_i32_e32 v131, 31, v130
	v_lshlrev_b64 v[132:133], 9, v[130:131]
	v_lshl_add_u64 v[132:133], s[38:39], 0, v[132:133]
	v_mad_i64_i32 v[130:131], s[0:1], v130, s2, v[152:153]
	v_lshl_add_u64 v[142:143], v[132:133], 0, v[154:155]
	v_lshl_add_u64 v[136:137], v[130:131], 0, s[18:19]
	v_pk_mul_f32 v[122:123], v[122:123], v[134:135] op_sel_hi:[1,0]
	v_pk_mul_f32 v[126:127], v[126:127], v[134:135] op_sel_hi:[1,0]
	v_pk_mul_f32 v[124:125], v[124:125], v[134:135] op_sel_hi:[1,0]
	v_pk_mul_f32 v[122:123], v[30:31], v[122:123]
	v_pk_mul_f32 v[128:129], v[128:129], v[134:135] op_sel_hi:[1,0]
	v_pk_mul_f32 v[126:127], v[26:27], v[126:127]
	v_pk_mul_f32 v[124:125], v[32:33], v[124:125]
	v_pk_mul_f32 v[128:129], v[28:29], v[128:129]
	v_cndmask_b32_e64 v144, v123, v127, s[36:37]
	ds_swizzle_b32 v146, v144 offset:swizzle(SWAP,16)
	v_cndmask_b32_e64 v144, v124, v128, s[36:37]
	ds_swizzle_b32 v147, v144 offset:swizzle(SWAP,16)
	v_cndmask_b32_e64 v144, v125, v129, s[36:37]
	ds_swizzle_b32 v148, v144 offset:swizzle(SWAP,16)
	s_waitcnt lgkmcnt(2)
	v_cndmask_b32_e64 v123, v146, v123, s[36:37]
	v_cndmask_b32_e64 v127, v127, v146, s[36:37]
	s_waitcnt lgkmcnt(1)
	v_cndmask_b32_e64 v144, v147, v124, s[36:37]
	v_cndmask_b32_e64 v135, v122, v126, s[36:37]
	s_waitcnt lgkmcnt(0)
	v_cndmask_b32_e64 v145, v148, v125, s[36:37]
	ds_swizzle_b32 v135, v135 offset:swizzle(SWAP,16)
	v_cndmask_b32_e64 v128, v128, v147, s[36:37]
	v_cndmask_b32_e64 v129, v129, v148, s[36:37]
	s_waitcnt lgkmcnt(0)
	v_cndmask_b32_e64 v122, v135, v122, s[36:37]
	v_cndmask_b32_e64 v126, v126, v135, s[36:37]
	v_pk_mul_f32 v[114:115], v[114:115], v[134:135] op_sel_hi:[1,0]
	v_pk_mul_f32 v[118:119], v[118:119], v[134:135] op_sel_hi:[1,0]
	v_pk_mul_f32 v[114:115], v[22:23], v[114:115]
	v_pk_mul_f32 v[118:119], v[18:19], v[118:119]
	v_pk_mul_f32 v[116:117], v[116:117], v[134:135] op_sel_hi:[1,0]
	v_pk_mul_f32 v[120:121], v[120:121], v[134:135] op_sel_hi:[1,0]
	v_pk_mul_f32 v[116:117], v[24:25], v[116:117]
	v_pk_mul_f32 v[120:121], v[20:21], v[120:121]
	s_waitcnt vmcnt(11)
	v_lshlrev_b32_e32 v124, 16, v192
	v_and_b32_e32 v125, 0xffff0000, v192
	v_mul_f32_e32 v130, 0xbfb8aa3b, v124
	v_exp_f32_e32 v130, v130
	s_nop 0
	v_add_f32_e32 v130, 1.0, v130
	v_rcp_f32_e32 v146, v130
	v_mul_f32_e32 v130, 0xbfb8aa3b, v125
	v_exp_f32_e32 v130, v130
	s_nop 0
	v_add_f32_e32 v130, 1.0, v130
	v_rcp_f32_e32 v147, v130
	s_nop 0
	v_pk_mul_f32 v[124:125], v[146:147], v[124:125]
	s_nop 0
	v_pk_mul_f32 v[122:123], v[124:125], v[122:123]
	s_nop 0
	v_cvt_pk_bf16_f32 v124, v122, v123
	v_lshlrev_b32_e32 v122, 16, v193
	v_mul_f32_e32 v125, 0xbfb8aa3b, v122
	v_exp_f32_e32 v125, v125
	v_and_b32_e32 v123, 0xffff0000, v193
	v_add_f32_e32 v125, 1.0, v125
	v_rcp_f32_e32 v130, v125
	v_mul_f32_e32 v125, 0xbfb8aa3b, v123
	v_exp_f32_e32 v125, v125
	s_nop 0
	v_add_f32_e32 v125, 1.0, v125
	v_rcp_f32_e32 v131, v125
	s_nop 0
	v_pk_mul_f32 v[122:123], v[130:131], v[122:123]
	s_nop 0
	v_pk_mul_f32 v[122:123], v[122:123], v[144:145]
	s_nop 0
	v_cvt_pk_bf16_f32 v125, v122, v123
	v_lshlrev_b32_e32 v122, 16, v194
	v_and_b32_e32 v123, 0xffff0000, v194
	v_mul_f32_e32 v130, 0xbfb8aa3b, v122
	v_mul_f32_e32 v131, 0xbfb8aa3b, v123
	v_exp_f32_e32 v130, v130
	v_exp_f32_e32 v131, v131
	v_add_f32_e32 v130, 1.0, v130
	v_add_f32_e32 v131, 1.0, v131
	v_rcp_f32_e32 v130, v130
	v_rcp_f32_e32 v131, v131
	s_nop 0
	v_pk_mul_f32 v[122:123], v[130:131], v[122:123]
	s_nop 0
	v_pk_mul_f32 v[122:123], v[122:123], v[126:127]
	s_nop 0
	v_cvt_pk_bf16_f32 v126, v122, v123
	v_lshlrev_b32_e32 v122, 16, v195
	v_mul_f32_e32 v127, 0xbfb8aa3b, v122
	v_exp_f32_e32 v127, v127
	v_and_b32_e32 v123, 0xffff0000, v195
	ds_read2_b32 v[132:133], v162 offset0:160 offset1:176
	v_add_f32_e32 v127, 1.0, v127
	v_rcp_f32_e32 v130, v127
	v_mul_f32_e32 v127, 0xbfb8aa3b, v123
	v_exp_f32_e32 v127, v127
	s_nop 0
	v_add_f32_e32 v127, 1.0, v127
	v_rcp_f32_e32 v131, v127
	s_nop 0
	v_pk_mul_f32 v[122:123], v[130:131], v[122:123]
	s_nop 0
	v_pk_mul_f32 v[122:123], v[122:123], v[128:129]
	v_cndmask_b32_e64 v128, v114, v118, s[36:37]
	v_cvt_pk_bf16_f32 v127, v122, v123
	v_lshl_add_u64 v[122:123], v[136:137], 0, v[138:139]
	global_store_dwordx4 v[122:123], v[124:127], off offset:2048
	ds_swizzle_b32 v128, v128 offset:swizzle(SWAP,16)
	v_cndmask_b32_e64 v129, v115, v119, s[36:37]
	ds_swizzle_b32 v129, v129 offset:swizzle(SWAP,16)
	s_waitcnt lgkmcnt(1)
	v_cndmask_b32_e64 v114, v128, v114, s[36:37]
	v_cndmask_b32_e64 v118, v118, v128, s[36:37]
	v_cndmask_b32_e64 v130, v116, v120, s[36:37]
	ds_swizzle_b32 v130, v130 offset:swizzle(SWAP,16)
	s_waitcnt lgkmcnt(1)
	v_cndmask_b32_e64 v115, v129, v115, s[36:37]
	v_cndmask_b32_e64 v119, v119, v129, s[36:37]
	v_cndmask_b32_e64 v131, v117, v121, s[36:37]
	ds_swizzle_b32 v131, v131 offset:swizzle(SWAP,16)
	s_waitcnt lgkmcnt(1)
	v_cndmask_b32_e64 v116, v130, v116, s[36:37]
	v_cndmask_b32_e64 v120, v120, v130, s[36:37]
	s_waitcnt lgkmcnt(0)
	v_cndmask_b32_e64 v117, v131, v117, s[36:37]
	v_cndmask_b32_e64 v121, v121, v131, s[36:37]
	s_waitcnt vmcnt(11)
	v_lshlrev_b32_e32 v128, 16, v196
	v_and_b32_e32 v129, 0xffff0000, v196
	v_mul_f32_e32 v124, 0xbfb8aa3b, v128
	v_exp_f32_e32 v124, v124
	s_nop 0
	v_add_f32_e32 v124, 1.0, v124
	v_rcp_f32_e32 v130, v124
	v_mul_f32_e32 v124, 0xbfb8aa3b, v129
	v_exp_f32_e32 v124, v124
	s_nop 0
	v_add_f32_e32 v124, 1.0, v124
	v_rcp_f32_e32 v131, v124
	v_lshlrev_b32_e32 v124, 16, v197
	v_and_b32_e32 v125, 0xffff0000, v197
	v_pk_mul_f32 v[128:129], v[130:131], v[128:129]
	s_nop 0
	v_pk_mul_f32 v[114:115], v[128:129], v[114:115]
	ds_read2_b32 v[130:131], v162 offset0:32 offset1:48
	v_cvt_pk_bf16_f32 v114, v114, v115
	v_mul_f32_e32 v115, 0xbfb8aa3b, v124
	v_exp_f32_e32 v115, v115
	s_nop 0
	v_add_f32_e32 v115, 1.0, v115
	v_rcp_f32_e32 v128, v115
	v_mul_f32_e32 v115, 0xbfb8aa3b, v125
	v_exp_f32_e32 v115, v115
	s_nop 0
	v_add_f32_e32 v115, 1.0, v115
	v_rcp_f32_e32 v129, v115
	s_nop 0
	v_pk_mul_f32 v[124:125], v[128:129], v[124:125]
	s_nop 0
	v_pk_mul_f32 v[116:117], v[124:125], v[116:117]
	ds_read2_b32 v[128:129], v160 offset0:160 offset1:176
	v_cvt_pk_bf16_f32 v115, v116, v117
	v_lshlrev_b32_e32 v116, 16, v198
	v_and_b32_e32 v117, 0xffff0000, v198
	v_mul_f32_e32 v124, 0xbfb8aa3b, v116
	v_mul_f32_e32 v125, 0xbfb8aa3b, v117
	v_exp_f32_e32 v124, v124
	v_exp_f32_e32 v125, v125
	v_add_f32_e32 v124, 1.0, v124
	v_add_f32_e32 v125, 1.0, v125
	v_rcp_f32_e32 v124, v124
	v_rcp_f32_e32 v125, v125
	s_nop 0
	v_pk_mul_f32 v[116:117], v[124:125], v[116:117]
	s_nop 0
	v_pk_mul_f32 v[116:117], v[116:117], v[118:119]
	v_lshlrev_b32_e32 v118, 16, v199
	v_cvt_pk_bf16_f32 v116, v116, v117
	v_mul_f32_e32 v117, 0xbfb8aa3b, v118
	v_exp_f32_e32 v117, v117
	v_and_b32_e32 v119, 0xffff0000, v199
	ds_read2_b32 v[126:127], v160 offset0:32 offset1:48
	v_add_f32_e32 v117, 1.0, v117
	v_rcp_f32_e32 v124, v117
	v_mul_f32_e32 v117, 0xbfb8aa3b, v119
	v_exp_f32_e32 v117, v117
	s_nop 0
	v_add_f32_e32 v117, 1.0, v117
	v_rcp_f32_e32 v125, v117
	s_nop 0
	v_pk_mul_f32 v[118:119], v[124:125], v[118:119]
	s_nop 0
	v_pk_mul_f32 v[118:119], v[118:119], v[120:121]
	ds_read2_b32 v[120:121], v186 offset0:160 offset1:176
	v_cvt_pk_bf16_f32 v117, v118, v119
	ds_read2_b32 v[118:119], v186 offset0:32 offset1:48
	global_store_dwordx4 v[122:123], v[114:117], off offset:2112
	ds_read2_b32 v[122:123], v158 offset0:32 offset1:48
	ds_read2_b32 v[124:125], v158 offset0:160 offset1:176
	s_waitcnt lgkmcnt(2)
	v_add_f32_e32 v114, 0, v118
	v_add_f32_e32 v114, v114, v120
	s_waitcnt lgkmcnt(1)
	v_add_f32_e32 v114, v114, v122
	s_waitcnt lgkmcnt(0)
	v_add_f32_e32 v114, v114, v124
	v_add_f32_e32 v114, v114, v126
	v_add_f32_e32 v114, v114, v128
	v_add_f32_e32 v114, v114, v130
	v_add_f32_e32 v114, v114, v132
	v_fmamk_f32 v114, v114, 0x3b000000, v172
	v_cmp_gt_f32_e32 vcc, s4, v114
	v_mul_f32_e32 v115, 0x4f800000, v114
	s_nop 0
	v_cndmask_b32_e32 v114, v114, v115, vcc
	v_sqrt_f32_e32 v115, v114
	s_nop 0
	v_add_u32_e32 v116, -1, v115
	v_fma_f32 v117, -v116, v115, v114
	v_cmp_ge_f32_e64 s[0:1], 0, v117
	v_add_u32_e32 v117, 1, v115
	s_nop 0
	v_cndmask_b32_e64 v116, v115, v116, s[0:1]
	v_fma_f32 v115, -v117, v115, v114
	v_cmp_lt_f32_e64 s[0:1], 0, v115
	s_nop 1
	v_cndmask_b32_e64 v115, v116, v117, s[0:1]
	v_mul_f32_e32 v116, 0x37800000, v115
	v_cndmask_b32_e32 v115, v115, v116, vcc
	v_cmp_class_f32_e32 vcc, v114, v173
	s_nop 1
	v_cndmask_b32_e32 v114, v115, v114, vcc
	v_div_scale_f32 v115, s[0:1], v114, v114, 1.0
	v_rcp_f32_e32 v116, v115
	s_nop 0
	v_fma_f32 v117, -v115, v116, 1.0
	v_fmac_f32_e32 v116, v117, v116
	v_div_scale_f32 v117, vcc, 1.0, v114, 1.0
	v_mul_f32_e32 v118, v117, v116
	v_fma_f32 v120, -v115, v118, v117
	v_fmac_f32_e32 v118, v120, v116
	v_fma_f32 v115, -v115, v118, v117
	v_div_fmas_f32 v115, v115, v116, v118
	v_div_fixup_f32 v118, v115, v114, 1.0
	v_or_b32_e32 v114, 32, v150
	v_ashrrev_i32_e32 v115, 31, v114
	v_lshlrev_b64 v[116:117], 9, v[114:115]
	v_lshl_add_u64 v[116:117], s[38:39], 0, v[116:117]
	v_mad_i64_i32 v[114:115], s[0:1], v114, s2, v[152:153]
	v_lshl_add_u64 v[136:137], v[116:117], 0, v[154:155]
	v_lshl_add_u64 v[134:135], v[114:115], 0, s[18:19]
	v_pk_mul_f32 v[108:109], v[108:109], v[118:119] op_sel_hi:[1,0]
	v_pk_mul_f32 v[112:113], v[112:113], v[118:119] op_sel_hi:[1,0]
	v_pk_mul_f32 v[108:109], v[32:33], v[108:109]
	v_pk_mul_f32 v[112:113], v[28:29], v[112:113]
	v_pk_mul_f32 v[106:107], v[106:107], v[118:119] op_sel_hi:[1,0]
	v_cndmask_b32_e64 v124, v108, v112, s[36:37]
	ds_swizzle_b32 v124, v124 offset:swizzle(SWAP,16)
	v_cndmask_b32_e64 v126, v109, v113, s[36:37]
	ds_swizzle_b32 v126, v126 offset:swizzle(SWAP,16)
	v_pk_mul_f32 v[110:111], v[110:111], v[118:119] op_sel_hi:[1,0]
	v_pk_mul_f32 v[106:107], v[30:31], v[106:107]
	s_waitcnt lgkmcnt(1)
	v_cndmask_b32_e64 v142, v124, v108, s[36:37]
	v_pk_mul_f32 v[110:111], v[26:27], v[110:111]
	s_waitcnt lgkmcnt(0)
	v_cndmask_b32_e64 v143, v126, v109, s[36:37]
	v_cndmask_b32_e64 v120, v106, v110, s[36:37]
	v_cndmask_b32_e64 v122, v107, v111, s[36:37]
	ds_swizzle_b32 v120, v120 offset:swizzle(SWAP,16)
	ds_swizzle_b32 v122, v122 offset:swizzle(SWAP,16)
	v_cndmask_b32_e64 v113, v113, v126, s[36:37]
	v_cndmask_b32_e64 v112, v112, v124, s[36:37]
	v_pk_mul_f32 v[98:99], v[98:99], v[118:119] op_sel_hi:[1,0]
	s_waitcnt lgkmcnt(1)
	v_cndmask_b32_e64 v106, v120, v106, s[36:37]
	s_waitcnt lgkmcnt(0)
	v_cndmask_b32_e64 v107, v122, v107, s[36:37]
	v_cndmask_b32_e64 v111, v111, v122, s[36:37]
	v_cndmask_b32_e64 v110, v110, v120, s[36:37]
	v_pk_mul_f32 v[102:103], v[102:103], v[118:119] op_sel_hi:[1,0]
	v_pk_mul_f32 v[98:99], v[22:23], v[98:99]
	v_pk_mul_f32 v[102:103], v[18:19], v[102:103]
	v_pk_mul_f32 v[100:101], v[100:101], v[118:119] op_sel_hi:[1,0]
	v_pk_mul_f32 v[104:105], v[104:105], v[118:119] op_sel_hi:[1,0]
	v_pk_mul_f32 v[100:101], v[24:25], v[100:101]
	v_pk_mul_f32 v[104:105], v[20:21], v[104:105]
	s_waitcnt vmcnt(11)
	v_lshlrev_b32_e32 v108, 16, v200
	v_and_b32_e32 v109, 0xffff0000, v200
	v_mul_f32_e32 v114, 0xbfb8aa3b, v108
	v_exp_f32_e32 v114, v114
	s_nop 0
	v_add_f32_e32 v114, 1.0, v114
	v_rcp_f32_e32 v144, v114
	v_mul_f32_e32 v114, 0xbfb8aa3b, v109
	v_exp_f32_e32 v114, v114
	s_nop 0
	v_add_f32_e32 v114, 1.0, v114
	v_rcp_f32_e32 v145, v114
	s_nop 0
	v_pk_mul_f32 v[108:109], v[144:145], v[108:109]
	s_nop 0
	v_pk_mul_f32 v[106:107], v[108:109], v[106:107]
	s_nop 0
	v_cvt_pk_bf16_f32 v108, v106, v107
	v_lshlrev_b32_e32 v106, 16, v201
	v_mul_f32_e32 v109, 0xbfb8aa3b, v106
	v_exp_f32_e32 v109, v109
	v_and_b32_e32 v107, 0xffff0000, v201
	v_add_f32_e32 v109, 1.0, v109
	v_rcp_f32_e32 v114, v109
	v_mul_f32_e32 v109, 0xbfb8aa3b, v107
	v_exp_f32_e32 v109, v109
	s_nop 0
	v_add_f32_e32 v109, 1.0, v109
	v_rcp_f32_e32 v115, v109
	s_nop 0
	v_pk_mul_f32 v[106:107], v[114:115], v[106:107]
	s_nop 0
	v_pk_mul_f32 v[106:107], v[106:107], v[142:143]
	s_nop 0
	v_cvt_pk_bf16_f32 v109, v106, v107
	v_lshlrev_b32_e32 v106, 16, v202
	v_and_b32_e32 v107, 0xffff0000, v202
	v_mul_f32_e32 v114, 0xbfb8aa3b, v106
	v_mul_f32_e32 v115, 0xbfb8aa3b, v107
	v_exp_f32_e32 v114, v114
	v_exp_f32_e32 v115, v115
	v_add_f32_e32 v114, 1.0, v114
	v_add_f32_e32 v115, 1.0, v115
	v_rcp_f32_e32 v114, v114
	v_rcp_f32_e32 v115, v115
	s_nop 0
	v_pk_mul_f32 v[106:107], v[114:115], v[106:107]
	s_nop 0
	v_pk_mul_f32 v[106:107], v[106:107], v[110:111]
	s_nop 0
	v_cvt_pk_bf16_f32 v110, v106, v107
	v_lshlrev_b32_e32 v106, 16, v203
	v_mul_f32_e32 v111, 0xbfb8aa3b, v106
	v_exp_f32_e32 v111, v111
	v_and_b32_e32 v107, 0xffff0000, v203
	v_add_f32_e32 v111, 1.0, v111
	v_rcp_f32_e32 v114, v111
	v_mul_f32_e32 v111, 0xbfb8aa3b, v107
	v_exp_f32_e32 v111, v111
	s_nop 0
	v_add_f32_e32 v111, 1.0, v111
	v_rcp_f32_e32 v115, v111
	s_nop 0
	v_pk_mul_f32 v[106:107], v[114:115], v[106:107]
	s_nop 0
	v_pk_mul_f32 v[106:107], v[106:107], v[112:113]
	v_cndmask_b32_e64 v112, v98, v102, s[36:37]
	v_cvt_pk_bf16_f32 v111, v106, v107
	v_lshl_add_u64 v[106:107], v[134:135], 0, v[138:139]
	global_store_dwordx4 v[106:107], v[108:111], off offset:2048
	ds_swizzle_b32 v112, v112 offset:swizzle(SWAP,16)
	v_cndmask_b32_e64 v113, v99, v103, s[36:37]
	ds_swizzle_b32 v113, v113 offset:swizzle(SWAP,16)
	s_waitcnt lgkmcnt(1)
	v_cndmask_b32_e64 v98, v112, v98, s[36:37]
	v_cndmask_b32_e64 v102, v102, v112, s[36:37]
	v_cndmask_b32_e64 v114, v100, v104, s[36:37]
	ds_swizzle_b32 v114, v114 offset:swizzle(SWAP,16)
	s_waitcnt lgkmcnt(1)
	v_cndmask_b32_e64 v99, v113, v99, s[36:37]
	v_cndmask_b32_e64 v103, v103, v113, s[36:37]
	v_cndmask_b32_e64 v115, v101, v105, s[36:37]
	ds_swizzle_b32 v115, v115 offset:swizzle(SWAP,16)
	s_waitcnt lgkmcnt(1)
	v_cndmask_b32_e64 v100, v114, v100, s[36:37]
	v_cndmask_b32_e64 v104, v104, v114, s[36:37]
	s_waitcnt lgkmcnt(0)
	v_cndmask_b32_e64 v101, v115, v101, s[36:37]
	v_cndmask_b32_e64 v105, v105, v115, s[36:37]
	s_waitcnt vmcnt(11)
	v_lshlrev_b32_e32 v112, 16, v204
	v_and_b32_e32 v113, 0xffff0000, v204
	v_mul_f32_e32 v108, 0xbfb8aa3b, v112
	v_exp_f32_e32 v108, v108
	s_nop 0
	v_add_f32_e32 v108, 1.0, v108
	v_rcp_f32_e32 v114, v108
	v_mul_f32_e32 v108, 0xbfb8aa3b, v113
	v_exp_f32_e32 v108, v108
	s_nop 0
	v_add_f32_e32 v108, 1.0, v108
	v_rcp_f32_e32 v115, v108
	v_lshlrev_b32_e32 v108, 16, v205
	v_and_b32_e32 v109, 0xffff0000, v205
	v_pk_mul_f32 v[112:113], v[114:115], v[112:113]
	s_nop 0
	v_pk_mul_f32 v[98:99], v[112:113], v[98:99]
	s_nop 0
	v_cvt_pk_bf16_f32 v98, v98, v99
	v_mul_f32_e32 v99, 0xbfb8aa3b, v108
	v_exp_f32_e32 v99, v99
	s_nop 0
	v_add_f32_e32 v99, 1.0, v99
	v_rcp_f32_e32 v112, v99
	v_mul_f32_e32 v99, 0xbfb8aa3b, v109
	v_exp_f32_e32 v99, v99
	s_nop 0
	v_add_f32_e32 v99, 1.0, v99
	v_rcp_f32_e32 v113, v99
	s_nop 0
	v_pk_mul_f32 v[108:109], v[112:113], v[108:109]
	s_nop 0
	v_pk_mul_f32 v[100:101], v[108:109], v[100:101]
	s_nop 0
	v_cvt_pk_bf16_f32 v99, v100, v101
	v_lshlrev_b32_e32 v100, 16, v206
	v_and_b32_e32 v101, 0xffff0000, v206
	v_mul_f32_e32 v108, 0xbfb8aa3b, v100
	v_mul_f32_e32 v109, 0xbfb8aa3b, v101
	v_exp_f32_e32 v108, v108
	v_exp_f32_e32 v109, v109
	v_add_f32_e32 v108, 1.0, v108
	v_add_f32_e32 v109, 1.0, v109
	v_rcp_f32_e32 v108, v108
	v_rcp_f32_e32 v109, v109
	s_nop 0
	v_pk_mul_f32 v[100:101], v[108:109], v[100:101]
	s_nop 0
	v_pk_mul_f32 v[100:101], v[100:101], v[102:103]
	v_lshlrev_b32_e32 v102, 16, v207
	v_cvt_pk_bf16_f32 v100, v100, v101
	v_mul_f32_e32 v101, 0xbfb8aa3b, v102
	v_exp_f32_e32 v101, v101
	v_and_b32_e32 v103, 0xffff0000, v207
	v_add_f32_e32 v101, 1.0, v101
	v_rcp_f32_e32 v108, v101
	v_mul_f32_e32 v101, 0xbfb8aa3b, v103
	v_exp_f32_e32 v101, v101
	s_nop 0
	v_add_f32_e32 v101, 1.0, v101
	v_rcp_f32_e32 v109, v101
	s_nop 0
	v_pk_mul_f32 v[102:103], v[108:109], v[102:103]
	s_nop 0
	v_pk_mul_f32 v[102:103], v[102:103], v[104:105]
	s_nop 0
	v_cvt_pk_bf16_f32 v101, v102, v103
	global_store_dwordx4 v[106:107], v[98:101], off offset:2112
	s_nop 1
	v_add_f32_e32 v98, 0, v119
	v_add_f32_e32 v98, v98, v121
	v_add_f32_e32 v98, v98, v123
	v_add_f32_e32 v98, v98, v125
	v_add_f32_e32 v98, v98, v127
	v_add_f32_e32 v98, v98, v129
	v_add_f32_e32 v98, v98, v131
	v_add_f32_e32 v98, v98, v133
	v_fmamk_f32 v98, v98, 0x3b000000, v172
	v_cmp_gt_f32_e32 vcc, s4, v98
	v_mul_f32_e32 v99, 0x4f800000, v98
	s_nop 0
	v_cndmask_b32_e32 v98, v98, v99, vcc
	v_sqrt_f32_e32 v99, v98
	s_nop 0
	v_add_u32_e32 v100, -1, v99
	v_fma_f32 v101, -v100, v99, v98
	v_cmp_ge_f32_e64 s[0:1], 0, v101
	v_add_u32_e32 v101, 1, v99
	s_nop 0
	v_cndmask_b32_e64 v100, v99, v100, s[0:1]
	v_fma_f32 v99, -v101, v99, v98
	v_cmp_lt_f32_e64 s[0:1], 0, v99
	s_nop 1
	v_cndmask_b32_e64 v99, v100, v101, s[0:1]
	v_mul_f32_e32 v100, 0x37800000, v99
	v_cndmask_b32_e32 v99, v99, v100, vcc
	v_cmp_class_f32_e32 vcc, v98, v173
	s_nop 1
	v_cndmask_b32_e32 v98, v99, v98, vcc
	v_div_scale_f32 v99, s[0:1], v98, v98, 1.0
	v_rcp_f32_e32 v100, v99
	s_nop 0
	v_fma_f32 v101, -v99, v100, 1.0
	v_fmac_f32_e32 v100, v101, v100
	v_div_scale_f32 v101, vcc, 1.0, v98, 1.0
	v_mul_f32_e32 v102, v101, v100
	v_fma_f32 v103, -v99, v102, v101
	v_fmac_f32_e32 v102, v103, v100
	v_fma_f32 v99, -v99, v102, v101
	v_div_fmas_f32 v99, v99, v100, v102
	v_div_fixup_f32 v102, v99, v98, 1.0
	v_or_b32_e32 v98, 48, v150
	v_ashrrev_i32_e32 v99, 31, v98
	v_lshlrev_b64 v[100:101], 9, v[98:99]
	v_lshl_add_u64 v[100:101], s[38:39], 0, v[100:101]
	v_mad_i64_i32 v[98:99], s[0:1], v98, s2, v[152:153]
	v_lshl_add_u64 v[106:107], v[100:101], 0, v[154:155]
	v_lshl_add_u64 v[104:105], v[98:99], 0, s[18:19]
	v_pk_mul_f32 v[90:91], v[90:91], v[102:103] op_sel_hi:[1,0]
	v_pk_mul_f32 v[94:95], v[94:95], v[102:103] op_sel_hi:[1,0]
	v_pk_mul_f32 v[92:93], v[92:93], v[102:103] op_sel_hi:[1,0]
	v_pk_mul_f32 v[90:91], v[30:31], v[90:91]
	v_pk_mul_f32 v[96:97], v[96:97], v[102:103] op_sel_hi:[1,0]
	v_pk_mul_f32 v[94:95], v[26:27], v[94:95]
	v_pk_mul_f32 v[92:93], v[32:33], v[92:93]
	v_pk_mul_f32 v[96:97], v[28:29], v[96:97]
	v_cndmask_b32_e64 v108, v91, v95, s[36:37]
	ds_swizzle_b32 v110, v108 offset:swizzle(SWAP,16)
	v_cndmask_b32_e64 v108, v92, v96, s[36:37]
	ds_swizzle_b32 v111, v108 offset:swizzle(SWAP,16)
	v_cndmask_b32_e64 v108, v93, v97, s[36:37]
	ds_swizzle_b32 v112, v108 offset:swizzle(SWAP,16)
	s_waitcnt lgkmcnt(2)
	v_cndmask_b32_e64 v91, v110, v91, s[36:37]
	v_cndmask_b32_e64 v95, v95, v110, s[36:37]
	s_waitcnt lgkmcnt(1)
	v_cndmask_b32_e64 v108, v111, v92, s[36:37]
	v_cndmask_b32_e64 v103, v90, v94, s[36:37]
	s_waitcnt lgkmcnt(0)
	v_cndmask_b32_e64 v109, v112, v93, s[36:37]
	ds_swizzle_b32 v103, v103 offset:swizzle(SWAP,16)
	v_cndmask_b32_e64 v96, v96, v111, s[36:37]
	v_cndmask_b32_e64 v97, v97, v112, s[36:37]
	s_waitcnt lgkmcnt(0)
	v_cndmask_b32_e64 v90, v103, v90, s[36:37]
	v_cndmask_b32_e64 v94, v94, v103, s[36:37]
	v_pk_mul_f32 v[82:83], v[82:83], v[102:103] op_sel_hi:[1,0]
	v_pk_mul_f32 v[86:87], v[86:87], v[102:103] op_sel_hi:[1,0]
	v_pk_mul_f32 v[82:83], v[22:23], v[82:83]
	v_pk_mul_f32 v[86:87], v[18:19], v[86:87]
	v_pk_mul_f32 v[84:85], v[84:85], v[102:103] op_sel_hi:[1,0]
	v_pk_mul_f32 v[88:89], v[88:89], v[102:103] op_sel_hi:[1,0]
	v_pk_mul_f32 v[84:85], v[24:25], v[84:85]
	v_pk_mul_f32 v[88:89], v[20:21], v[88:89]
	s_waitcnt vmcnt(11)
	v_lshlrev_b32_e32 v92, 16, v208
	v_and_b32_e32 v93, 0xffff0000, v208
	v_mul_f32_e32 v98, 0xbfb8aa3b, v92
	v_exp_f32_e32 v98, v98
	s_nop 0
	v_add_f32_e32 v98, 1.0, v98
	v_rcp_f32_e32 v110, v98
	v_mul_f32_e32 v98, 0xbfb8aa3b, v93
	v_exp_f32_e32 v98, v98
	s_nop 0
	v_add_f32_e32 v98, 1.0, v98
	v_rcp_f32_e32 v111, v98
	s_nop 0
	v_pk_mul_f32 v[92:93], v[110:111], v[92:93]
	s_nop 0
	v_pk_mul_f32 v[90:91], v[92:93], v[90:91]
	s_nop 0
	v_cvt_pk_bf16_f32 v92, v90, v91
	v_lshlrev_b32_e32 v90, 16, v209
	v_mul_f32_e32 v93, 0xbfb8aa3b, v90
	v_exp_f32_e32 v93, v93
	v_and_b32_e32 v91, 0xffff0000, v209
	v_add_f32_e32 v93, 1.0, v93
	v_rcp_f32_e32 v98, v93
	v_mul_f32_e32 v93, 0xbfb8aa3b, v91
	v_exp_f32_e32 v93, v93
	s_nop 0
	v_add_f32_e32 v93, 1.0, v93
	v_rcp_f32_e32 v99, v93
	s_nop 0
	v_pk_mul_f32 v[90:91], v[98:99], v[90:91]
	s_nop 0
	v_pk_mul_f32 v[90:91], v[90:91], v[108:109]
	s_nop 0
	v_cvt_pk_bf16_f32 v93, v90, v91
	v_lshlrev_b32_e32 v90, 16, v210
	v_and_b32_e32 v91, 0xffff0000, v210
	v_mul_f32_e32 v98, 0xbfb8aa3b, v90
	v_mul_f32_e32 v99, 0xbfb8aa3b, v91
	v_exp_f32_e32 v98, v98
	v_exp_f32_e32 v99, v99
	v_add_f32_e32 v98, 1.0, v98
	v_add_f32_e32 v99, 1.0, v99
	v_rcp_f32_e32 v98, v98
	v_rcp_f32_e32 v99, v99
	s_nop 0
	v_pk_mul_f32 v[90:91], v[98:99], v[90:91]
	s_nop 0
	v_pk_mul_f32 v[90:91], v[90:91], v[94:95]
	s_nop 0
	v_cvt_pk_bf16_f32 v94, v90, v91
	v_lshlrev_b32_e32 v90, 16, v211
	v_mul_f32_e32 v95, 0xbfb8aa3b, v90
	v_exp_f32_e32 v95, v95
	v_and_b32_e32 v91, 0xffff0000, v211
	ds_read2_b32 v[100:101], v162 offset0:192 offset1:208
	v_add_f32_e32 v95, 1.0, v95
	v_rcp_f32_e32 v98, v95
	v_mul_f32_e32 v95, 0xbfb8aa3b, v91
	v_exp_f32_e32 v95, v95
	s_nop 0
	v_add_f32_e32 v95, 1.0, v95
	v_rcp_f32_e32 v99, v95
	s_nop 0
	v_pk_mul_f32 v[90:91], v[98:99], v[90:91]
	s_nop 0
	v_pk_mul_f32 v[90:91], v[90:91], v[96:97]
	v_cndmask_b32_e64 v96, v82, v86, s[36:37]
	v_cvt_pk_bf16_f32 v95, v90, v91
	v_lshl_add_u64 v[90:91], v[104:105], 0, v[138:139]
	global_store_dwordx4 v[90:91], v[92:95], off offset:2048
	ds_swizzle_b32 v96, v96 offset:swizzle(SWAP,16)
	v_cndmask_b32_e64 v97, v83, v87, s[36:37]
	ds_swizzle_b32 v97, v97 offset:swizzle(SWAP,16)
	s_waitcnt lgkmcnt(1)
	v_cndmask_b32_e64 v82, v96, v82, s[36:37]
	v_cndmask_b32_e64 v86, v86, v96, s[36:37]
	v_cndmask_b32_e64 v98, v84, v88, s[36:37]
	ds_swizzle_b32 v98, v98 offset:swizzle(SWAP,16)
	s_waitcnt lgkmcnt(1)
	v_cndmask_b32_e64 v83, v97, v83, s[36:37]
	v_cndmask_b32_e64 v87, v87, v97, s[36:37]
	v_cndmask_b32_e64 v99, v85, v89, s[36:37]
	ds_swizzle_b32 v99, v99 offset:swizzle(SWAP,16)
	s_waitcnt lgkmcnt(1)
	v_cndmask_b32_e64 v84, v98, v84, s[36:37]
	v_cndmask_b32_e64 v88, v88, v98, s[36:37]
	s_waitcnt lgkmcnt(0)
	v_cndmask_b32_e64 v85, v99, v85, s[36:37]
	v_cndmask_b32_e64 v89, v89, v99, s[36:37]
	s_waitcnt vmcnt(11)
	v_lshlrev_b32_e32 v96, 16, v212
	v_and_b32_e32 v97, 0xffff0000, v212
	v_mul_f32_e32 v92, 0xbfb8aa3b, v96
	v_exp_f32_e32 v92, v92
	s_nop 0
	v_add_f32_e32 v92, 1.0, v92
	v_rcp_f32_e32 v98, v92
	v_mul_f32_e32 v92, 0xbfb8aa3b, v97
	v_exp_f32_e32 v92, v92
	s_nop 0
	v_add_f32_e32 v92, 1.0, v92
	v_rcp_f32_e32 v99, v92
	v_lshlrev_b32_e32 v92, 16, v213
	v_and_b32_e32 v93, 0xffff0000, v213
	v_pk_mul_f32 v[96:97], v[98:99], v[96:97]
	s_nop 0
	v_pk_mul_f32 v[82:83], v[96:97], v[82:83]
	ds_read2_b32 v[98:99], v162 offset0:64 offset1:80
	v_cvt_pk_bf16_f32 v82, v82, v83
	v_mul_f32_e32 v83, 0xbfb8aa3b, v92
	v_exp_f32_e32 v83, v83
	s_nop 0
	v_add_f32_e32 v83, 1.0, v83
	v_rcp_f32_e32 v96, v83
	v_mul_f32_e32 v83, 0xbfb8aa3b, v93
	v_exp_f32_e32 v83, v83
	s_nop 0
	v_add_f32_e32 v83, 1.0, v83
	v_rcp_f32_e32 v97, v83
	s_nop 0
	v_pk_mul_f32 v[92:93], v[96:97], v[92:93]
	s_nop 0
	v_pk_mul_f32 v[84:85], v[92:93], v[84:85]
	ds_read2_b32 v[96:97], v160 offset0:192 offset1:208
	v_cvt_pk_bf16_f32 v83, v84, v85
	v_lshlrev_b32_e32 v84, 16, v214
	v_and_b32_e32 v85, 0xffff0000, v214
	v_mul_f32_e32 v92, 0xbfb8aa3b, v84
	v_mul_f32_e32 v93, 0xbfb8aa3b, v85
	v_exp_f32_e32 v92, v92
	v_exp_f32_e32 v93, v93
	v_add_f32_e32 v92, 1.0, v92
	v_add_f32_e32 v93, 1.0, v93
	v_rcp_f32_e32 v92, v92
	v_rcp_f32_e32 v93, v93
	s_nop 0
	v_pk_mul_f32 v[84:85], v[92:93], v[84:85]
	s_nop 0
	v_pk_mul_f32 v[84:85], v[84:85], v[86:87]
	v_lshlrev_b32_e32 v86, 16, v215
	v_cvt_pk_bf16_f32 v84, v84, v85
	v_mul_f32_e32 v85, 0xbfb8aa3b, v86
	v_exp_f32_e32 v85, v85
	v_and_b32_e32 v87, 0xffff0000, v215
	ds_read2_b32 v[94:95], v160 offset0:64 offset1:80
	v_add_f32_e32 v85, 1.0, v85
	v_rcp_f32_e32 v92, v85
	v_mul_f32_e32 v85, 0xbfb8aa3b, v87
	v_exp_f32_e32 v85, v85
	s_nop 0
	v_add_f32_e32 v85, 1.0, v85
	v_rcp_f32_e32 v93, v85
	s_nop 0
	v_pk_mul_f32 v[86:87], v[92:93], v[86:87]
	s_nop 0
	v_pk_mul_f32 v[86:87], v[86:87], v[88:89]
	ds_read2_b32 v[88:89], v186 offset0:192 offset1:208
	v_cvt_pk_bf16_f32 v85, v86, v87
	ds_read2_b32 v[86:87], v186 offset0:64 offset1:80
	global_store_dwordx4 v[90:91], v[82:85], off offset:2112
	ds_read2_b32 v[90:91], v158 offset0:64 offset1:80
	ds_read2_b32 v[92:93], v158 offset0:192 offset1:208
	s_waitcnt lgkmcnt(2)
	v_add_f32_e32 v82, 0, v86
	v_add_f32_e32 v82, v82, v88
	s_waitcnt lgkmcnt(1)
	v_add_f32_e32 v82, v82, v90
	s_waitcnt lgkmcnt(0)
	v_add_f32_e32 v82, v82, v92
	v_add_f32_e32 v82, v82, v94
	v_add_f32_e32 v82, v82, v96
	v_add_f32_e32 v82, v82, v98
	v_add_f32_e32 v82, v82, v100
	v_fmamk_f32 v82, v82, 0x3b000000, v172
	v_cmp_gt_f32_e32 vcc, s4, v82
	v_mul_f32_e32 v83, 0x4f800000, v82
	s_nop 0
	v_cndmask_b32_e32 v82, v82, v83, vcc
	v_sqrt_f32_e32 v83, v82
	s_nop 0
	v_add_u32_e32 v84, -1, v83
	v_fma_f32 v85, -v84, v83, v82
	v_cmp_ge_f32_e64 s[0:1], 0, v85
	v_add_u32_e32 v85, 1, v83
	s_nop 0
	v_cndmask_b32_e64 v84, v83, v84, s[0:1]
	v_fma_f32 v83, -v85, v83, v82
	v_cmp_lt_f32_e64 s[0:1], 0, v83
	s_nop 1
	v_cndmask_b32_e64 v83, v84, v85, s[0:1]
	v_mul_f32_e32 v84, 0x37800000, v83
	v_cndmask_b32_e32 v83, v83, v84, vcc
	v_cmp_class_f32_e32 vcc, v82, v173
	s_nop 1
	v_cndmask_b32_e32 v82, v83, v82, vcc
	v_div_scale_f32 v83, s[0:1], v82, v82, 1.0
	v_rcp_f32_e32 v84, v83
	s_nop 0
	v_fma_f32 v85, -v83, v84, 1.0
	v_fmac_f32_e32 v84, v85, v84
	v_div_scale_f32 v85, vcc, 1.0, v82, 1.0
	v_mul_f32_e32 v86, v85, v84
	v_fma_f32 v88, -v83, v86, v85
	v_fmac_f32_e32 v86, v88, v84
	v_fma_f32 v83, -v83, v86, v85
	v_div_fmas_f32 v83, v83, v84, v86
	v_div_fixup_f32 v86, v83, v82, 1.0
	v_or_b32_e32 v82, 64, v150
	v_ashrrev_i32_e32 v83, 31, v82
	v_lshlrev_b64 v[84:85], 9, v[82:83]
	v_lshl_add_u64 v[84:85], s[38:39], 0, v[84:85]
	v_mad_i64_i32 v[82:83], s[0:1], v82, s2, v[152:153]
	v_lshl_add_u64 v[104:105], v[84:85], 0, v[154:155]
	v_lshl_add_u64 v[102:103], v[82:83], 0, s[18:19]
	v_pk_mul_f32 v[76:77], v[76:77], v[86:87] op_sel_hi:[1,0]
	v_pk_mul_f32 v[80:81], v[80:81], v[86:87] op_sel_hi:[1,0]
	v_pk_mul_f32 v[76:77], v[32:33], v[76:77]
	v_pk_mul_f32 v[80:81], v[28:29], v[80:81]
	v_pk_mul_f32 v[74:75], v[74:75], v[86:87] op_sel_hi:[1,0]
	v_cndmask_b32_e64 v92, v76, v80, s[36:37]
	ds_swizzle_b32 v92, v92 offset:swizzle(SWAP,16)
	v_cndmask_b32_e64 v94, v77, v81, s[36:37]
	ds_swizzle_b32 v94, v94 offset:swizzle(SWAP,16)
	v_pk_mul_f32 v[78:79], v[78:79], v[86:87] op_sel_hi:[1,0]
	v_pk_mul_f32 v[74:75], v[30:31], v[74:75]
	s_waitcnt lgkmcnt(1)
	v_cndmask_b32_e64 v106, v92, v76, s[36:37]
	v_pk_mul_f32 v[78:79], v[26:27], v[78:79]
	s_waitcnt lgkmcnt(0)
	v_cndmask_b32_e64 v107, v94, v77, s[36:37]
	v_cndmask_b32_e64 v88, v74, v78, s[36:37]
	v_cndmask_b32_e64 v90, v75, v79, s[36:37]
	ds_swizzle_b32 v88, v88 offset:swizzle(SWAP,16)
	ds_swizzle_b32 v90, v90 offset:swizzle(SWAP,16)
	v_cndmask_b32_e64 v81, v81, v94, s[36:37]
	v_cndmask_b32_e64 v80, v80, v92, s[36:37]
	v_pk_mul_f32 v[70:71], v[70:71], v[86:87] op_sel_hi:[1,0]
	s_waitcnt lgkmcnt(1)
	v_cndmask_b32_e64 v74, v88, v74, s[36:37]
	s_waitcnt lgkmcnt(0)
	v_cndmask_b32_e64 v75, v90, v75, s[36:37]
	v_cndmask_b32_e64 v79, v79, v90, s[36:37]
	v_cndmask_b32_e64 v78, v78, v88, s[36:37]
	v_pk_mul_f32 v[66:67], v[66:67], v[86:87] op_sel_hi:[1,0]
	v_pk_mul_f32 v[70:71], v[22:23], v[70:71]
	v_pk_mul_f32 v[66:67], v[18:19], v[66:67]
	v_pk_mul_f32 v[72:73], v[72:73], v[86:87] op_sel_hi:[1,0]
	v_pk_mul_f32 v[68:69], v[68:69], v[86:87] op_sel_hi:[1,0]
	v_pk_mul_f32 v[72:73], v[24:25], v[72:73]
	v_pk_mul_f32 v[68:69], v[20:21], v[68:69]
	s_waitcnt vmcnt(11)
	v_lshlrev_b32_e32 v76, 16, v216
	v_and_b32_e32 v77, 0xffff0000, v216
	v_mul_f32_e32 v82, 0xbfb8aa3b, v76
	v_exp_f32_e32 v82, v82
	s_nop 0
	v_add_f32_e32 v82, 1.0, v82
	v_rcp_f32_e32 v108, v82
	v_mul_f32_e32 v82, 0xbfb8aa3b, v77
	v_exp_f32_e32 v82, v82
	s_nop 0
	v_add_f32_e32 v82, 1.0, v82
	v_rcp_f32_e32 v109, v82
	s_nop 0
	v_pk_mul_f32 v[76:77], v[108:109], v[76:77]
	s_nop 0
	v_pk_mul_f32 v[74:75], v[76:77], v[74:75]
	s_nop 0
	v_cvt_pk_bf16_f32 v76, v74, v75
	v_lshlrev_b32_e32 v74, 16, v217
	v_mul_f32_e32 v77, 0xbfb8aa3b, v74
	v_exp_f32_e32 v77, v77
	v_and_b32_e32 v75, 0xffff0000, v217
	v_add_f32_e32 v77, 1.0, v77
	v_rcp_f32_e32 v82, v77
	v_mul_f32_e32 v77, 0xbfb8aa3b, v75
	v_exp_f32_e32 v77, v77
	s_nop 0
	v_add_f32_e32 v77, 1.0, v77
	v_rcp_f32_e32 v83, v77
	s_nop 0
	v_pk_mul_f32 v[74:75], v[82:83], v[74:75]
	s_nop 0
	v_pk_mul_f32 v[74:75], v[74:75], v[106:107]
	s_nop 0
	v_cvt_pk_bf16_f32 v77, v74, v75
	v_lshlrev_b32_e32 v74, 16, v218
	v_and_b32_e32 v75, 0xffff0000, v218
	v_mul_f32_e32 v82, 0xbfb8aa3b, v74
	v_mul_f32_e32 v83, 0xbfb8aa3b, v75
	v_exp_f32_e32 v82, v82
	v_exp_f32_e32 v83, v83
	v_add_f32_e32 v82, 1.0, v82
	v_add_f32_e32 v83, 1.0, v83
	v_rcp_f32_e32 v82, v82
	v_rcp_f32_e32 v83, v83
	s_nop 0
	v_pk_mul_f32 v[74:75], v[82:83], v[74:75]
	s_nop 0
	v_pk_mul_f32 v[74:75], v[74:75], v[78:79]
	s_nop 0
	v_cvt_pk_bf16_f32 v78, v74, v75
	v_lshlrev_b32_e32 v74, 16, v219
	v_mul_f32_e32 v79, 0xbfb8aa3b, v74
	v_exp_f32_e32 v79, v79
	v_and_b32_e32 v75, 0xffff0000, v219
	v_add_f32_e32 v79, 1.0, v79
	v_rcp_f32_e32 v82, v79
	v_mul_f32_e32 v79, 0xbfb8aa3b, v75
	v_exp_f32_e32 v79, v79
	s_nop 0
	v_add_f32_e32 v79, 1.0, v79
	v_rcp_f32_e32 v83, v79
	s_nop 0
	v_pk_mul_f32 v[74:75], v[82:83], v[74:75]
	s_nop 0
	v_pk_mul_f32 v[74:75], v[74:75], v[80:81]
	v_cndmask_b32_e64 v80, v70, v66, s[36:37]
	v_cvt_pk_bf16_f32 v79, v74, v75
	v_lshl_add_u64 v[74:75], v[102:103], 0, v[138:139]
	global_store_dwordx4 v[74:75], v[76:79], off offset:2048
	ds_swizzle_b32 v82, v80 offset:swizzle(SWAP,16)
	v_cndmask_b32_e64 v80, v71, v67, s[36:37]
	ds_swizzle_b32 v83, v80 offset:swizzle(SWAP,16)
	v_cndmask_b32_e64 v80, v72, v68, s[36:37]
	ds_swizzle_b32 v80, v80 offset:swizzle(SWAP,16)
	v_cndmask_b32_e64 v81, v73, v69, s[36:37]
	ds_swizzle_b32 v81, v81 offset:swizzle(SWAP,16)
	s_waitcnt lgkmcnt(3)
	v_cndmask_b32_e64 v70, v82, v70, s[36:37]
	s_waitcnt lgkmcnt(2)
	v_cndmask_b32_e64 v71, v83, v71, s[36:37]
	s_waitcnt lgkmcnt(1)
	v_cndmask_b32_e64 v72, v80, v72, s[36:37]
	v_cndmask_b32_e64 v80, v68, v80, s[36:37]
	v_cndmask_b32_e64 v68, v66, v82, s[36:37]
	s_waitcnt lgkmcnt(0)
	v_cndmask_b32_e64 v73, v81, v73, s[36:37]
	v_cndmask_b32_e64 v81, v69, v81, s[36:37]
	v_cndmask_b32_e64 v69, v67, v83, s[36:37]
	s_waitcnt vmcnt(11)
	v_lshlrev_b32_e32 v66, 16, v220
	v_and_b32_e32 v67, 0xffff0000, v220
	v_mul_f32_e32 v76, 0xbfb8aa3b, v66
	v_exp_f32_e32 v76, v76
	s_nop 0
	v_add_f32_e32 v76, 1.0, v76
	v_rcp_f32_e32 v82, v76
	v_mul_f32_e32 v76, 0xbfb8aa3b, v67
	v_exp_f32_e32 v76, v76
	s_nop 0
	v_add_f32_e32 v76, 1.0, v76
	v_rcp_f32_e32 v83, v76
	s_nop 0
	v_pk_mul_f32 v[66:67], v[82:83], v[66:67]
	s_nop 0
	v_pk_mul_f32 v[66:67], v[66:67], v[70:71]
	v_lshlrev_b32_e32 v70, 16, v221
	v_cvt_pk_bf16_f32 v66, v66, v67
	v_mul_f32_e32 v67, 0xbfb8aa3b, v70
	v_exp_f32_e32 v67, v67
	v_and_b32_e32 v71, 0xffff0000, v221
	v_add_f32_e32 v67, 1.0, v67
	v_rcp_f32_e32 v76, v67
	v_mul_f32_e32 v67, 0xbfb8aa3b, v71
	v_exp_f32_e32 v67, v67
	s_nop 0
	v_add_f32_e32 v67, 1.0, v67
	v_rcp_f32_e32 v77, v67
	s_nop 0
	v_pk_mul_f32 v[70:71], v[76:77], v[70:71]
	s_nop 0
	v_pk_mul_f32 v[70:71], v[70:71], v[72:73]
	s_nop 0
	v_cvt_pk_bf16_f32 v67, v70, v71
	v_lshlrev_b32_e32 v70, 16, v222
	v_and_b32_e32 v71, 0xffff0000, v222
	v_mul_f32_e32 v72, 0xbfb8aa3b, v70
	v_mul_f32_e32 v73, 0xbfb8aa3b, v71
	v_exp_f32_e32 v72, v72
	v_exp_f32_e32 v73, v73
	v_add_f32_e32 v72, 1.0, v72
	v_add_f32_e32 v73, 1.0, v73
	v_rcp_f32_e32 v72, v72
	v_rcp_f32_e32 v73, v73
	s_nop 0
	v_pk_mul_f32 v[70:71], v[72:73], v[70:71]
	s_nop 0
	v_pk_mul_f32 v[68:69], v[70:71], v[68:69]
	v_lshlrev_b32_e32 v70, 16, v223
	v_cvt_pk_bf16_f32 v68, v68, v69
	v_mul_f32_e32 v69, 0xbfb8aa3b, v70
	v_exp_f32_e32 v69, v69
	v_and_b32_e32 v71, 0xffff0000, v223
	v_add_f32_e32 v69, 1.0, v69
	v_rcp_f32_e32 v72, v69
	v_mul_f32_e32 v69, 0xbfb8aa3b, v71
	v_exp_f32_e32 v69, v69
	s_nop 0
	v_add_f32_e32 v69, 1.0, v69
	v_rcp_f32_e32 v73, v69
	s_nop 0
	v_pk_mul_f32 v[70:71], v[72:73], v[70:71]
	s_nop 0
	v_pk_mul_f32 v[70:71], v[70:71], v[80:81]
	s_nop 0
	v_cvt_pk_bf16_f32 v69, v70, v71
	global_store_dwordx4 v[74:75], v[66:69], off offset:2112
	s_nop 1
	v_add_f32_e32 v66, 0, v87
	v_add_f32_e32 v66, v66, v89
	v_add_f32_e32 v66, v66, v91
	v_add_f32_e32 v66, v66, v93
	v_add_f32_e32 v66, v66, v95
	v_add_f32_e32 v66, v66, v97
	v_add_f32_e32 v66, v66, v99
	v_add_f32_e32 v66, v66, v101
	v_fmamk_f32 v66, v66, 0x3b000000, v172
	v_cmp_gt_f32_e32 vcc, s4, v66
	v_mul_f32_e32 v67, 0x4f800000, v66
	s_nop 0
	v_cndmask_b32_e32 v66, v66, v67, vcc
	v_sqrt_f32_e32 v67, v66
	s_nop 0
	v_add_u32_e32 v68, -1, v67
	v_fma_f32 v69, -v68, v67, v66
	v_cmp_ge_f32_e64 s[0:1], 0, v69
	v_add_u32_e32 v69, 1, v67
	s_nop 0
	v_cndmask_b32_e64 v68, v67, v68, s[0:1]
	v_fma_f32 v67, -v69, v67, v66
	v_cmp_lt_f32_e64 s[0:1], 0, v67
	s_nop 1
	v_cndmask_b32_e64 v67, v68, v69, s[0:1]
	v_mul_f32_e32 v68, 0x37800000, v67
	v_cndmask_b32_e32 v67, v67, v68, vcc
	v_cmp_class_f32_e32 vcc, v66, v173
	s_nop 1
	v_cndmask_b32_e32 v66, v67, v66, vcc
	v_div_scale_f32 v67, s[0:1], v66, v66, 1.0
	v_rcp_f32_e32 v68, v67
	s_nop 0
	v_fma_f32 v69, -v67, v68, 1.0
	v_fmac_f32_e32 v68, v69, v68
	v_div_scale_f32 v69, vcc, 1.0, v66, 1.0
	v_mul_f32_e32 v70, v69, v68
	v_fma_f32 v71, -v67, v70, v69
	v_fmac_f32_e32 v70, v71, v68
	v_fma_f32 v67, -v67, v70, v69
	v_div_fmas_f32 v67, v67, v68, v70
	v_div_fixup_f32 v70, v67, v66, 1.0
	v_or_b32_e32 v66, 0x50, v150
	v_ashrrev_i32_e32 v67, 31, v66
	v_lshlrev_b64 v[68:69], 9, v[66:67]
	v_lshl_add_u64 v[68:69], s[38:39], 0, v[68:69]
	v_mad_i64_i32 v[66:67], s[0:1], v66, s2, v[152:153]
	v_lshl_add_u64 v[74:75], v[68:69], 0, v[154:155]
	v_lshl_add_u64 v[72:73], v[66:67], 0, s[18:19]
	v_pk_mul_f32 v[58:59], v[58:59], v[70:71] op_sel_hi:[1,0]
	v_pk_mul_f32 v[62:63], v[62:63], v[70:71] op_sel_hi:[1,0]
	v_pk_mul_f32 v[60:61], v[60:61], v[70:71] op_sel_hi:[1,0]
	v_pk_mul_f32 v[58:59], v[30:31], v[58:59]
	v_pk_mul_f32 v[64:65], v[64:65], v[70:71] op_sel_hi:[1,0]
	v_pk_mul_f32 v[62:63], v[26:27], v[62:63]
	v_pk_mul_f32 v[60:61], v[32:33], v[60:61]
	v_pk_mul_f32 v[64:65], v[28:29], v[64:65]
	v_cndmask_b32_e64 v76, v59, v63, s[36:37]
	ds_swizzle_b32 v78, v76 offset:swizzle(SWAP,16)
	v_cndmask_b32_e64 v76, v60, v64, s[36:37]
	ds_swizzle_b32 v79, v76 offset:swizzle(SWAP,16)
	v_cndmask_b32_e64 v76, v61, v65, s[36:37]
	ds_swizzle_b32 v80, v76 offset:swizzle(SWAP,16)
	s_waitcnt lgkmcnt(2)
	v_cndmask_b32_e64 v59, v78, v59, s[36:37]
	v_cndmask_b32_e64 v63, v63, v78, s[36:37]
	s_waitcnt lgkmcnt(1)
	v_cndmask_b32_e64 v76, v79, v60, s[36:37]
	v_cndmask_b32_e64 v71, v58, v62, s[36:37]
	s_waitcnt lgkmcnt(0)
	v_cndmask_b32_e64 v77, v80, v61, s[36:37]
	ds_swizzle_b32 v71, v71 offset:swizzle(SWAP,16)
	v_cndmask_b32_e64 v64, v64, v79, s[36:37]
	v_cndmask_b32_e64 v65, v65, v80, s[36:37]
	s_waitcnt lgkmcnt(0)
	v_cndmask_b32_e64 v58, v71, v58, s[36:37]
	v_cndmask_b32_e64 v62, v62, v71, s[36:37]
	v_pk_mul_f32 v[54:55], v[54:55], v[70:71] op_sel_hi:[1,0]
	v_pk_mul_f32 v[50:51], v[50:51], v[70:71] op_sel_hi:[1,0]
	v_pk_mul_f32 v[54:55], v[22:23], v[54:55]
	v_pk_mul_f32 v[50:51], v[18:19], v[50:51]
	v_pk_mul_f32 v[56:57], v[56:57], v[70:71] op_sel_hi:[1,0]
	v_pk_mul_f32 v[52:53], v[52:53], v[70:71] op_sel_hi:[1,0]
	v_pk_mul_f32 v[56:57], v[24:25], v[56:57]
	v_pk_mul_f32 v[52:53], v[20:21], v[52:53]
	s_waitcnt vmcnt(11)
	v_lshlrev_b32_e32 v60, 16, v224
	v_and_b32_e32 v61, 0xffff0000, v224
	v_mul_f32_e32 v66, 0xbfb8aa3b, v60
	v_exp_f32_e32 v66, v66
	s_nop 0
	v_add_f32_e32 v66, 1.0, v66
	v_rcp_f32_e32 v78, v66
	v_mul_f32_e32 v66, 0xbfb8aa3b, v61
	v_exp_f32_e32 v66, v66
	s_nop 0
	v_add_f32_e32 v66, 1.0, v66
	v_rcp_f32_e32 v79, v66
	s_nop 0
	v_pk_mul_f32 v[60:61], v[78:79], v[60:61]
	s_nop 0
	v_pk_mul_f32 v[58:59], v[60:61], v[58:59]
	s_nop 0
	v_cvt_pk_bf16_f32 v60, v58, v59
	v_lshlrev_b32_e32 v58, 16, v225
	v_mul_f32_e32 v61, 0xbfb8aa3b, v58
	v_exp_f32_e32 v61, v61
	v_and_b32_e32 v59, 0xffff0000, v225
	v_add_f32_e32 v61, 1.0, v61
	v_rcp_f32_e32 v66, v61
	v_mul_f32_e32 v61, 0xbfb8aa3b, v59
	v_exp_f32_e32 v61, v61
	s_nop 0
	v_add_f32_e32 v61, 1.0, v61
	v_rcp_f32_e32 v67, v61
	s_nop 0
	v_pk_mul_f32 v[58:59], v[66:67], v[58:59]
	s_nop 0
	v_pk_mul_f32 v[58:59], v[58:59], v[76:77]
	s_nop 0
	v_cvt_pk_bf16_f32 v61, v58, v59
	v_lshlrev_b32_e32 v58, 16, v226
	v_and_b32_e32 v59, 0xffff0000, v226
	v_mul_f32_e32 v66, 0xbfb8aa3b, v58
	v_mul_f32_e32 v67, 0xbfb8aa3b, v59
	v_exp_f32_e32 v66, v66
	v_exp_f32_e32 v67, v67
	v_add_f32_e32 v66, 1.0, v66
	v_add_f32_e32 v67, 1.0, v67
	v_rcp_f32_e32 v66, v66
	v_rcp_f32_e32 v67, v67
	s_nop 0
	v_pk_mul_f32 v[58:59], v[66:67], v[58:59]
	s_nop 0
	v_pk_mul_f32 v[58:59], v[58:59], v[62:63]
	s_nop 0
	v_cvt_pk_bf16_f32 v62, v58, v59
	v_lshlrev_b32_e32 v58, 16, v227
	v_mul_f32_e32 v63, 0xbfb8aa3b, v58
	v_exp_f32_e32 v63, v63
	v_and_b32_e32 v59, 0xffff0000, v227
	ds_read2_b32 v[68:69], v162 offset0:224 offset1:240
	v_add_f32_e32 v63, 1.0, v63
	v_rcp_f32_e32 v66, v63
	v_mul_f32_e32 v63, 0xbfb8aa3b, v59
	v_exp_f32_e32 v63, v63
	s_nop 0
	v_add_f32_e32 v63, 1.0, v63
	v_rcp_f32_e32 v67, v63
	s_nop 0
	v_pk_mul_f32 v[58:59], v[66:67], v[58:59]
	s_nop 0
	v_pk_mul_f32 v[58:59], v[58:59], v[64:65]
	v_cndmask_b32_e64 v64, v54, v50, s[36:37]
	v_cvt_pk_bf16_f32 v63, v58, v59
	v_lshl_add_u64 v[58:59], v[72:73], 0, v[138:139]
	global_store_dwordx4 v[58:59], v[60:63], off offset:2048
	ds_swizzle_b32 v66, v64 offset:swizzle(SWAP,16)
	v_cndmask_b32_e64 v64, v55, v51, s[36:37]
	ds_swizzle_b32 v67, v64 offset:swizzle(SWAP,16)
	v_cndmask_b32_e64 v64, v56, v52, s[36:37]
	ds_swizzle_b32 v64, v64 offset:swizzle(SWAP,16)
	v_cndmask_b32_e64 v65, v57, v53, s[36:37]
	ds_swizzle_b32 v65, v65 offset:swizzle(SWAP,16)
	s_waitcnt lgkmcnt(3)
	v_cndmask_b32_e64 v54, v66, v54, s[36:37]
	s_waitcnt lgkmcnt(2)
	v_cndmask_b32_e64 v55, v67, v55, s[36:37]
	s_waitcnt lgkmcnt(1)
	v_cndmask_b32_e64 v56, v64, v56, s[36:37]
	v_cndmask_b32_e64 v64, v52, v64, s[36:37]
	v_cndmask_b32_e64 v52, v50, v66, s[36:37]
	s_waitcnt lgkmcnt(0)
	v_cndmask_b32_e64 v57, v65, v57, s[36:37]
	v_cndmask_b32_e64 v65, v53, v65, s[36:37]
	v_cndmask_b32_e64 v53, v51, v67, s[36:37]
	s_waitcnt vmcnt(11)
	v_lshlrev_b32_e32 v50, 16, v228
	v_and_b32_e32 v51, 0xffff0000, v228
	v_mul_f32_e32 v60, 0xbfb8aa3b, v50
	v_exp_f32_e32 v60, v60
	s_nop 0
	v_add_f32_e32 v60, 1.0, v60
	v_rcp_f32_e32 v66, v60
	v_mul_f32_e32 v60, 0xbfb8aa3b, v51
	v_exp_f32_e32 v60, v60
	s_nop 0
	v_add_f32_e32 v60, 1.0, v60
	v_rcp_f32_e32 v67, v60
	s_nop 0
	v_pk_mul_f32 v[50:51], v[66:67], v[50:51]
	s_nop 0
	v_pk_mul_f32 v[50:51], v[50:51], v[54:55]
	v_lshlrev_b32_e32 v54, 16, v229
	v_cvt_pk_bf16_f32 v50, v50, v51
	v_mul_f32_e32 v51, 0xbfb8aa3b, v54
	v_exp_f32_e32 v51, v51
	v_and_b32_e32 v55, 0xffff0000, v229
	ds_read2_b32 v[66:67], v162 offset0:96 offset1:112
	v_add_f32_e32 v51, 1.0, v51
	v_rcp_f32_e32 v60, v51
	v_mul_f32_e32 v51, 0xbfb8aa3b, v55
	v_exp_f32_e32 v51, v51
	s_nop 0
	v_add_f32_e32 v51, 1.0, v51
	v_rcp_f32_e32 v61, v51
	s_nop 0
	v_pk_mul_f32 v[54:55], v[60:61], v[54:55]
	s_nop 0
	v_pk_mul_f32 v[54:55], v[54:55], v[56:57]
	ds_read2_b32 v[60:61], v158 offset0:224 offset1:240
	v_cvt_pk_bf16_f32 v51, v54, v55
	v_lshlrev_b32_e32 v54, 16, v230
	v_and_b32_e32 v55, 0xffff0000, v230
	v_mul_f32_e32 v56, 0xbfb8aa3b, v54
	v_mul_f32_e32 v57, 0xbfb8aa3b, v55
	v_exp_f32_e32 v56, v56
	v_exp_f32_e32 v57, v57
	v_add_f32_e32 v56, 1.0, v56
	v_add_f32_e32 v57, 1.0, v57
	v_rcp_f32_e32 v56, v56
	v_rcp_f32_e32 v57, v57
	s_nop 0
	v_pk_mul_f32 v[54:55], v[56:57], v[54:55]
	s_nop 0
	v_pk_mul_f32 v[52:53], v[54:55], v[52:53]
	v_lshlrev_b32_e32 v54, 16, v231
	v_cvt_pk_bf16_f32 v52, v52, v53
	v_mul_f32_e32 v53, 0xbfb8aa3b, v54
	v_exp_f32_e32 v53, v53
	v_and_b32_e32 v55, 0xffff0000, v231
	ds_read2_b32 v[62:63], v160 offset0:96 offset1:112
	v_add_f32_e32 v53, 1.0, v53
	v_rcp_f32_e32 v56, v53
	v_mul_f32_e32 v53, 0xbfb8aa3b, v55
	v_exp_f32_e32 v53, v53
	s_nop 0
	v_add_f32_e32 v53, 1.0, v53
	v_rcp_f32_e32 v57, v53
	s_nop 0
	v_pk_mul_f32 v[54:55], v[56:57], v[54:55]
	s_nop 0
	v_pk_mul_f32 v[54:55], v[54:55], v[64:65]
	ds_read2_b32 v[56:57], v186 offset0:224 offset1:240
	v_cvt_pk_bf16_f32 v53, v54, v55
	ds_read2_b32 v[54:55], v186 offset0:96 offset1:112
	global_store_dwordx4 v[58:59], v[50:53], off offset:2112
	ds_read2_b32 v[58:59], v158 offset0:96 offset1:112
	ds_read2_b32 v[64:65], v160 offset0:224 offset1:240
	s_waitcnt lgkmcnt(2)
	v_add_f32_e32 v50, 0, v54
	v_add_f32_e32 v50, v50, v56
	s_waitcnt lgkmcnt(1)
	v_add_f32_e32 v50, v50, v58
	v_add_f32_e32 v50, v50, v60
	v_add_f32_e32 v50, v50, v62
	s_waitcnt lgkmcnt(0)
	v_add_f32_e32 v50, v50, v64
	v_add_f32_e32 v50, v50, v66
	v_add_f32_e32 v50, v50, v68
	v_fmamk_f32 v50, v50, 0x3b000000, v172
	v_cmp_gt_f32_e32 vcc, s4, v50
	v_mul_f32_e32 v51, 0x4f800000, v50
	s_nop 0
	v_cndmask_b32_e32 v50, v50, v51, vcc
	v_sqrt_f32_e32 v51, v50
	s_nop 0
	v_add_u32_e32 v52, -1, v51
	v_fma_f32 v53, -v52, v51, v50
	v_cmp_ge_f32_e64 s[0:1], 0, v53
	v_add_u32_e32 v53, 1, v51
	s_nop 0
	v_cndmask_b32_e64 v52, v51, v52, s[0:1]
	v_fma_f32 v51, -v53, v51, v50
	v_cmp_lt_f32_e64 s[0:1], 0, v51
	s_nop 1
	v_cndmask_b32_e64 v51, v52, v53, s[0:1]
	v_mul_f32_e32 v52, 0x37800000, v51
	v_cndmask_b32_e32 v51, v51, v52, vcc
	v_cmp_class_f32_e32 vcc, v50, v173
	s_nop 1
	v_cndmask_b32_e32 v50, v51, v50, vcc
	v_div_scale_f32 v51, s[0:1], v50, v50, 1.0
	v_rcp_f32_e32 v52, v51
	s_nop 0
	v_fma_f32 v53, -v51, v52, 1.0
	v_fmac_f32_e32 v52, v53, v52
	v_div_scale_f32 v53, vcc, 1.0, v50, 1.0
	v_mul_f32_e32 v54, v53, v52
	v_fma_f32 v56, -v51, v54, v53
	v_fmac_f32_e32 v54, v56, v52
	v_fma_f32 v51, -v51, v54, v53
	v_div_fmas_f32 v51, v51, v52, v54
	v_div_fixup_f32 v54, v51, v50, 1.0
	v_or_b32_e32 v50, 0x60, v150
	v_ashrrev_i32_e32 v51, 31, v50
	v_lshlrev_b64 v[52:53], 9, v[50:51]
	v_lshl_add_u64 v[52:53], s[38:39], 0, v[52:53]
	v_mad_i64_i32 v[50:51], s[0:1], v50, s2, v[152:153]
	v_lshl_add_u64 v[72:73], v[52:53], 0, v[154:155]
	v_lshl_add_u64 v[70:71], v[50:51], 0, s[18:19]
	v_lshl_add_u64 v[50:51], v[72:73], 0, v[0:1]
	global_load_dwordx4 v[50:53], v[50:51], off nt
	v_pk_mul_f32 v[48:49], v[48:49], v[54:55] op_sel_hi:[1,0]
	v_pk_mul_f32 v[44:45], v[44:45], v[54:55] op_sel_hi:[1,0]
	v_pk_mul_f32 v[48:49], v[32:33], v[48:49]
	v_pk_mul_f32 v[44:45], v[28:29], v[44:45]
	v_pk_mul_f32 v[46:47], v[46:47], v[54:55] op_sel_hi:[1,0]
	v_cndmask_b32_e64 v60, v48, v44, s[36:37]
	ds_swizzle_b32 v60, v60 offset:swizzle(SWAP,16)
	v_cndmask_b32_e64 v62, v49, v45, s[36:37]
	ds_swizzle_b32 v62, v62 offset:swizzle(SWAP,16)
	v_pk_mul_f32 v[42:43], v[42:43], v[54:55] op_sel_hi:[1,0]
	v_pk_mul_f32 v[46:47], v[30:31], v[46:47]
	s_waitcnt lgkmcnt(1)
	v_cndmask_b32_e64 v74, v44, v60, s[36:37]
	v_pk_mul_f32 v[42:43], v[26:27], v[42:43]
	s_waitcnt lgkmcnt(0)
	v_cndmask_b32_e64 v75, v45, v62, s[36:37]
	v_cndmask_b32_e64 v56, v46, v42, s[36:37]
	v_cndmask_b32_e64 v58, v47, v43, s[36:37]
	ds_swizzle_b32 v56, v56 offset:swizzle(SWAP,16)
	ds_swizzle_b32 v58, v58 offset:swizzle(SWAP,16)
	v_cndmask_b32_e64 v49, v62, v49, s[36:37]
	v_cndmask_b32_e64 v48, v60, v48, s[36:37]
	v_pk_mul_f32 v[38:39], v[38:39], v[54:55] op_sel_hi:[1,0]
	s_waitcnt lgkmcnt(1)
	v_cndmask_b32_e64 v46, v56, v46, s[36:37]
	s_waitcnt lgkmcnt(0)
	v_cndmask_b32_e64 v47, v58, v47, s[36:37]
	v_cndmask_b32_e64 v43, v43, v58, s[36:37]
	v_cndmask_b32_e64 v42, v42, v56, s[36:37]
	v_pk_mul_f32 v[34:35], v[34:35], v[54:55] op_sel_hi:[1,0]
	v_pk_mul_f32 v[38:39], v[22:23], v[38:39]
	v_pk_mul_f32 v[34:35], v[18:19], v[34:35]
	v_pk_mul_f32 v[40:41], v[40:41], v[54:55] op_sel_hi:[1,0]
	v_pk_mul_f32 v[36:37], v[36:37], v[54:55] op_sel_hi:[1,0]
	v_pk_mul_f32 v[40:41], v[24:25], v[40:41]
	v_pk_mul_f32 v[36:37], v[20:21], v[36:37]
	s_waitcnt vmcnt(0)
	v_lshlrev_b32_e32 v44, 16, v50
	v_and_b32_e32 v45, 0xffff0000, v50
	v_mul_f32_e32 v50, 0xbfb8aa3b, v44
	v_exp_f32_e32 v50, v50
	s_nop 0
	v_add_f32_e32 v50, 1.0, v50
	v_rcp_f32_e32 v76, v50
	v_mul_f32_e32 v50, 0xbfb8aa3b, v45
	v_exp_f32_e32 v50, v50
	s_nop 0
	v_add_f32_e32 v50, 1.0, v50
	v_rcp_f32_e32 v77, v50
	s_nop 0
	v_pk_mul_f32 v[44:45], v[76:77], v[44:45]
	s_nop 0
	v_pk_mul_f32 v[44:45], v[44:45], v[46:47]
	v_lshlrev_b32_e32 v46, 16, v51
	v_cvt_pk_bf16_f32 v44, v44, v45
	v_mul_f32_e32 v45, 0xbfb8aa3b, v46
	v_exp_f32_e32 v45, v45
	v_and_b32_e32 v47, 0xffff0000, v51
	v_add_f32_e32 v45, 1.0, v45
	v_rcp_f32_e32 v50, v45
	v_mul_f32_e32 v45, 0xbfb8aa3b, v47
	v_exp_f32_e32 v45, v45
	s_nop 0
	v_add_f32_e32 v45, 1.0, v45
	v_rcp_f32_e32 v51, v45
	s_nop 0
	v_pk_mul_f32 v[46:47], v[50:51], v[46:47]
	s_nop 0
	v_pk_mul_f32 v[46:47], v[46:47], v[48:49]
	s_nop 0
	v_cvt_pk_bf16_f32 v45, v46, v47
	v_lshlrev_b32_e32 v46, 16, v52
	v_and_b32_e32 v47, 0xffff0000, v52
	v_mul_f32_e32 v48, 0xbfb8aa3b, v46
	v_mul_f32_e32 v49, 0xbfb8aa3b, v47
	v_exp_f32_e32 v48, v48
	v_exp_f32_e32 v49, v49
	v_add_f32_e32 v48, 1.0, v48
	v_add_f32_e32 v49, 1.0, v49
	v_rcp_f32_e32 v48, v48
	v_rcp_f32_e32 v49, v49
	s_nop 0
	v_pk_mul_f32 v[46:47], v[48:49], v[46:47]
	s_nop 0
	v_pk_mul_f32 v[42:43], v[46:47], v[42:43]
	s_nop 0
	v_cvt_pk_bf16_f32 v46, v42, v43
	v_lshlrev_b32_e32 v42, 16, v53
	v_mul_f32_e32 v47, 0xbfb8aa3b, v42
	v_exp_f32_e32 v47, v47
	v_and_b32_e32 v43, 0xffff0000, v53
	v_add_f32_e32 v47, 1.0, v47
	v_rcp_f32_e32 v48, v47
	v_mul_f32_e32 v47, 0xbfb8aa3b, v43
	v_exp_f32_e32 v47, v47
	s_nop 0
	v_add_f32_e32 v47, 1.0, v47
	v_rcp_f32_e32 v49, v47
	s_nop 0
	v_pk_mul_f32 v[42:43], v[48:49], v[42:43]
	s_nop 0
	v_pk_mul_f32 v[42:43], v[42:43], v[74:75]
	v_cndmask_b32_e64 v48, v38, v34, s[36:37]
	v_cvt_pk_bf16_f32 v47, v42, v43
	v_lshl_add_u64 v[42:43], v[70:71], 0, v[138:139]
	global_store_dwordx4 v[42:43], v[44:47], off offset:2048
	ds_swizzle_b32 v50, v48 offset:swizzle(SWAP,16)
	v_cndmask_b32_e64 v48, v39, v35, s[36:37]
	v_lshl_add_u64 v[44:45], v[72:73], 0, v[140:141]
	global_load_dwordx4 v[44:47], v[44:45], off nt
	ds_swizzle_b32 v51, v48 offset:swizzle(SWAP,16)
	v_cndmask_b32_e64 v48, v40, v36, s[36:37]
	ds_swizzle_b32 v48, v48 offset:swizzle(SWAP,16)
	v_cndmask_b32_e64 v49, v41, v37, s[36:37]
	ds_swizzle_b32 v49, v49 offset:swizzle(SWAP,16)
	s_waitcnt lgkmcnt(3)
	v_cndmask_b32_e64 v38, v50, v38, s[36:37]
	s_waitcnt lgkmcnt(2)
	v_cndmask_b32_e64 v39, v51, v39, s[36:37]
	s_waitcnt lgkmcnt(1)
	v_cndmask_b32_e64 v40, v48, v40, s[36:37]
	v_cndmask_b32_e64 v48, v36, v48, s[36:37]
	v_cndmask_b32_e64 v36, v34, v50, s[36:37]
	s_waitcnt lgkmcnt(0)
	v_cndmask_b32_e64 v41, v49, v41, s[36:37]
	v_cndmask_b32_e64 v49, v37, v49, s[36:37]
	v_cndmask_b32_e64 v37, v35, v51, s[36:37]
	s_waitcnt vmcnt(0)
	v_lshlrev_b32_e32 v34, 16, v44
	v_and_b32_e32 v35, 0xffff0000, v44
	v_mul_f32_e32 v44, 0xbfb8aa3b, v34
	v_exp_f32_e32 v44, v44
	s_nop 0
	v_add_f32_e32 v44, 1.0, v44
	v_rcp_f32_e32 v50, v44
	v_mul_f32_e32 v44, 0xbfb8aa3b, v35
	v_exp_f32_e32 v44, v44
	s_nop 0
	v_add_f32_e32 v44, 1.0, v44
	v_rcp_f32_e32 v51, v44
	s_nop 0
	v_pk_mul_f32 v[34:35], v[50:51], v[34:35]
	s_nop 0
	v_pk_mul_f32 v[34:35], v[34:35], v[38:39]
	v_lshlrev_b32_e32 v38, 16, v45
	v_cvt_pk_bf16_f32 v34, v34, v35
	v_mul_f32_e32 v35, 0xbfb8aa3b, v38
	v_exp_f32_e32 v35, v35
	v_and_b32_e32 v39, 0xffff0000, v45
	v_add_f32_e32 v35, 1.0, v35
	v_rcp_f32_e32 v44, v35
	v_mul_f32_e32 v35, 0xbfb8aa3b, v39
	v_exp_f32_e32 v35, v35
	s_nop 0
	v_add_f32_e32 v35, 1.0, v35
	v_rcp_f32_e32 v45, v35
	s_nop 0
	v_pk_mul_f32 v[38:39], v[44:45], v[38:39]
	s_nop 0
	v_pk_mul_f32 v[38:39], v[38:39], v[40:41]
	s_nop 0
	v_cvt_pk_bf16_f32 v35, v38, v39
	v_lshlrev_b32_e32 v38, 16, v46
	v_and_b32_e32 v39, 0xffff0000, v46
	v_mul_f32_e32 v40, 0xbfb8aa3b, v38
	v_mul_f32_e32 v41, 0xbfb8aa3b, v39
	v_exp_f32_e32 v40, v40
	v_exp_f32_e32 v41, v41
	v_add_f32_e32 v40, 1.0, v40
	v_add_f32_e32 v41, 1.0, v41
	v_rcp_f32_e32 v40, v40
	v_rcp_f32_e32 v41, v41
	s_nop 0
	v_pk_mul_f32 v[38:39], v[40:41], v[38:39]
	s_nop 0
	v_pk_mul_f32 v[36:37], v[38:39], v[36:37]
	v_lshlrev_b32_e32 v38, 16, v47
	v_cvt_pk_bf16_f32 v36, v36, v37
	v_mul_f32_e32 v37, 0xbfb8aa3b, v38
	v_exp_f32_e32 v37, v37
	v_and_b32_e32 v39, 0xffff0000, v47
	v_add_f32_e32 v37, 1.0, v37
	v_rcp_f32_e32 v40, v37
	v_mul_f32_e32 v37, 0xbfb8aa3b, v39
	v_exp_f32_e32 v37, v37
	s_nop 0
	v_add_f32_e32 v37, 1.0, v37
	v_rcp_f32_e32 v41, v37
	s_nop 0
	v_pk_mul_f32 v[38:39], v[40:41], v[38:39]
	s_nop 0
	v_pk_mul_f32 v[38:39], v[38:39], v[48:49]
	s_nop 0
	v_cvt_pk_bf16_f32 v37, v38, v39
	global_store_dwordx4 v[42:43], v[34:37], off offset:2112
	s_nop 1
	v_add_f32_e32 v34, 0, v55
	v_add_f32_e32 v34, v34, v57
	v_add_f32_e32 v34, v34, v59
	v_add_f32_e32 v34, v34, v61
	v_add_f32_e32 v34, v34, v63
	v_add_f32_e32 v34, v34, v65
	v_add_f32_e32 v34, v34, v67
	v_add_f32_e32 v34, v34, v69
	v_fmamk_f32 v34, v34, 0x3b000000, v172
	v_cmp_gt_f32_e32 vcc, s4, v34
	v_mul_f32_e32 v35, 0x4f800000, v34
	s_nop 0
	v_cndmask_b32_e32 v34, v34, v35, vcc
	v_sqrt_f32_e32 v35, v34
	s_nop 0
	v_add_u32_e32 v36, -1, v35
	v_fma_f32 v37, -v36, v35, v34
	v_cmp_ge_f32_e64 s[0:1], 0, v37
	v_add_u32_e32 v37, 1, v35
	s_nop 0
	v_cndmask_b32_e64 v36, v35, v36, s[0:1]
	v_fma_f32 v35, -v37, v35, v34
	v_cmp_lt_f32_e64 s[0:1], 0, v35
	s_nop 1
	v_cndmask_b32_e64 v35, v36, v37, s[0:1]
	v_mul_f32_e32 v36, 0x37800000, v35
	v_cndmask_b32_e32 v35, v35, v36, vcc
	v_cmp_class_f32_e32 vcc, v34, v173
	s_nop 1
	v_cndmask_b32_e32 v34, v35, v34, vcc
	v_div_scale_f32 v35, s[0:1], v34, v34, 1.0
	v_rcp_f32_e32 v36, v35
	s_nop 0
	v_fma_f32 v37, -v35, v36, 1.0
	v_fmac_f32_e32 v36, v37, v36
	v_div_scale_f32 v37, vcc, 1.0, v34, 1.0
	v_mul_f32_e32 v38, v37, v36
	v_fma_f32 v39, -v35, v38, v37
	v_fmac_f32_e32 v38, v39, v36
	v_fma_f32 v35, -v35, v38, v37
	v_div_fmas_f32 v35, v35, v36, v38
	v_div_fixup_f32 v38, v35, v34, 1.0
	v_or_b32_e32 v34, 0x70, v150
	v_ashrrev_i32_e32 v35, 31, v34
	v_lshlrev_b64 v[36:37], 9, v[34:35]
	v_lshl_add_u64 v[36:37], s[38:39], 0, v[36:37]
	v_mad_i64_i32 v[34:35], s[0:1], v34, s2, v[152:153]
	v_lshl_add_u64 v[42:43], v[36:37], 0, v[154:155]
	v_lshl_add_u64 v[40:41], v[34:35], 0, s[18:19]
	v_lshl_add_u64 v[34:35], v[42:43], 0, v[0:1]
	global_load_dwordx4 v[34:37], v[34:35], off nt
	v_pk_mul_f32 v[14:15], v[14:15], v[38:39] op_sel_hi:[1,0]
	v_pk_mul_f32 v[10:11], v[10:11], v[38:39] op_sel_hi:[1,0]
	v_pk_mul_f32 v[16:17], v[16:17], v[38:39] op_sel_hi:[1,0]
	v_pk_mul_f32 v[14:15], v[30:31], v[14:15]
	v_pk_mul_f32 v[12:13], v[12:13], v[38:39] op_sel_hi:[1,0]
	v_pk_mul_f32 v[10:11], v[26:27], v[10:11]
	v_pk_mul_f32 v[16:17], v[32:33], v[16:17]
	v_pk_mul_f32 v[12:13], v[28:29], v[12:13]
	v_cndmask_b32_e64 v26, v15, v11, s[36:37]
	ds_swizzle_b32 v28, v26 offset:swizzle(SWAP,16)
	v_cndmask_b32_e64 v26, v16, v12, s[36:37]
	v_cndmask_b32_e64 v0, v14, v10, s[36:37]
	ds_swizzle_b32 v26, v26 offset:swizzle(SWAP,16)
	ds_swizzle_b32 v0, v0 offset:swizzle(SWAP,16)
	v_cndmask_b32_e64 v27, v17, v13, s[36:37]
	ds_swizzle_b32 v27, v27 offset:swizzle(SWAP,16)
	s_waitcnt lgkmcnt(3)
	v_cndmask_b32_e64 v15, v28, v15, s[36:37]
	s_waitcnt lgkmcnt(2)
	v_cndmask_b32_e64 v16, v26, v16, s[36:37]
	v_cndmask_b32_e64 v26, v12, v26, s[36:37]
	s_waitcnt lgkmcnt(1)
	v_cndmask_b32_e64 v14, v0, v14, s[36:37]
	v_cndmask_b32_e64 v10, v10, v0, s[36:37]
	s_waitcnt lgkmcnt(0)
	v_cndmask_b32_e64 v17, v27, v17, s[36:37]
	v_cndmask_b32_e64 v27, v13, v27, s[36:37]
	v_cndmask_b32_e64 v11, v11, v28, s[36:37]
	v_pk_mul_f32 v[6:7], v[6:7], v[38:39] op_sel_hi:[1,0]
	v_pk_mul_f32 v[2:3], v[2:3], v[38:39] op_sel_hi:[1,0]
	v_pk_mul_f32 v[8:9], v[8:9], v[38:39] op_sel_hi:[1,0]
	v_pk_mul_f32 v[6:7], v[22:23], v[6:7]
	v_pk_mul_f32 v[4:5], v[4:5], v[38:39] op_sel_hi:[1,0]
	v_pk_mul_f32 v[2:3], v[18:19], v[2:3]
	v_pk_mul_f32 v[8:9], v[24:25], v[8:9]
	v_pk_mul_f32 v[4:5], v[20:21], v[4:5]
	v_readlane_b32 s0, v254, 19
	s_add_i32 s14, s14, s0
	v_readlane_b32 s0, v252, 13
	v_readlane_b32 s1, v252, 14
	s_add_u32 s48, s48, s0
	s_addc_u32 s49, s49, s1
	s_cmpk_gt_i32 s15, 0xff
	s_waitcnt vmcnt(0)
	v_lshlrev_b32_e32 v12, 16, v34
	v_mul_f32_e32 v0, 0xbfb8aa3b, v12
	v_exp_f32_e32 v0, v0
	v_and_b32_e32 v13, 0xffff0000, v34
	v_add_f32_e32 v0, 1.0, v0
	v_rcp_f32_e32 v28, v0
	v_mul_f32_e32 v0, 0xbfb8aa3b, v13
	v_exp_f32_e32 v0, v0
	s_nop 0
	v_add_f32_e32 v0, 1.0, v0
	v_rcp_f32_e32 v29, v0
	s_nop 0
	v_pk_mul_f32 v[12:13], v[28:29], v[12:13]
	s_nop 0
	v_pk_mul_f32 v[12:13], v[12:13], v[14:15]
	v_lshlrev_b32_e32 v14, 16, v35
	v_mul_f32_e32 v0, 0xbfb8aa3b, v14
	v_exp_f32_e32 v0, v0
	v_and_b32_e32 v15, 0xffff0000, v35
	v_cvt_pk_bf16_f32 v12, v12, v13
	v_add_f32_e32 v0, 1.0, v0
	v_rcp_f32_e32 v28, v0
	v_mul_f32_e32 v0, 0xbfb8aa3b, v15
	v_exp_f32_e32 v0, v0
	s_nop 0
	v_add_f32_e32 v0, 1.0, v0
	v_rcp_f32_e32 v29, v0
	s_nop 0
	v_pk_mul_f32 v[14:15], v[28:29], v[14:15]
	s_nop 0
	v_pk_mul_f32 v[14:15], v[14:15], v[16:17]
	s_nop 0
	v_cvt_pk_bf16_f32 v13, v14, v15
	v_lshlrev_b32_e32 v14, 16, v36
	v_mul_f32_e32 v0, 0xbfb8aa3b, v14
	v_exp_f32_e32 v0, v0
	v_and_b32_e32 v15, 0xffff0000, v36
	v_add_f32_e32 v0, 1.0, v0
	v_rcp_f32_e32 v16, v0
	v_mul_f32_e32 v0, 0xbfb8aa3b, v15
	v_exp_f32_e32 v0, v0
	s_nop 0
	v_add_f32_e32 v0, 1.0, v0
	v_rcp_f32_e32 v17, v0
	s_nop 0
	v_pk_mul_f32 v[14:15], v[16:17], v[14:15]
	s_nop 0
	v_pk_mul_f32 v[10:11], v[14:15], v[10:11]
	s_nop 0
	v_cvt_pk_bf16_f32 v14, v10, v11
	v_lshlrev_b32_e32 v10, 16, v37
	v_mul_f32_e32 v0, 0xbfb8aa3b, v10
	v_exp_f32_e32 v0, v0
	v_and_b32_e32 v11, 0xffff0000, v37
	v_add_f32_e32 v0, 1.0, v0
	v_rcp_f32_e32 v16, v0
	v_mul_f32_e32 v0, 0xbfb8aa3b, v11
	v_exp_f32_e32 v0, v0
	s_nop 0
	v_add_f32_e32 v0, 1.0, v0
	v_rcp_f32_e32 v17, v0
	v_cndmask_b32_e64 v0, v6, v2, s[36:37]
	ds_swizzle_b32 v0, v0 offset:swizzle(SWAP,16)
	v_pk_mul_f32 v[10:11], v[16:17], v[10:11]
	s_nop 0
	v_pk_mul_f32 v[10:11], v[10:11], v[26:27]
	v_cndmask_b32_e64 v16, v7, v3, s[36:37]
	v_cvt_pk_bf16_f32 v15, v10, v11
	v_lshl_add_u64 v[10:11], v[40:41], 0, v[138:139]
	global_store_dwordx4 v[10:11], v[12:15], off offset:2048
	ds_swizzle_b32 v18, v16 offset:swizzle(SWAP,16)
	v_cndmask_b32_e64 v16, v8, v4, s[36:37]
	v_lshl_add_u64 v[12:13], v[42:43], 0, v[140:141]
	global_load_dwordx4 v[12:15], v[12:13], off nt
	ds_swizzle_b32 v16, v16 offset:swizzle(SWAP,16)
	v_cndmask_b32_e64 v17, v9, v5, s[36:37]
	ds_swizzle_b32 v17, v17 offset:swizzle(SWAP,16)
	s_waitcnt lgkmcnt(3)
	v_cndmask_b32_e64 v6, v0, v6, s[36:37]
	s_waitcnt lgkmcnt(2)
	v_cndmask_b32_e64 v7, v18, v7, s[36:37]
	s_waitcnt lgkmcnt(1)
	v_cndmask_b32_e64 v8, v16, v8, s[36:37]
	v_cndmask_b32_e64 v16, v4, v16, s[36:37]
	v_cndmask_b32_e64 v4, v2, v0, s[36:37]
	s_waitcnt lgkmcnt(0)
	v_cndmask_b32_e64 v9, v17, v9, s[36:37]
	v_cndmask_b32_e64 v17, v5, v17, s[36:37]
	v_cndmask_b32_e64 v5, v3, v18, s[36:37]
	s_waitcnt vmcnt(0)
	v_lshlrev_b32_e32 v2, 16, v12
	v_mul_f32_e32 v0, 0xbfb8aa3b, v2
	v_exp_f32_e32 v0, v0
	v_and_b32_e32 v3, 0xffff0000, v12
	v_add_f32_e32 v0, 1.0, v0
	v_rcp_f32_e32 v18, v0
	v_mul_f32_e32 v0, 0xbfb8aa3b, v3
	v_exp_f32_e32 v0, v0
	s_nop 0
	v_add_f32_e32 v0, 1.0, v0
	v_rcp_f32_e32 v19, v0
	s_nop 0
	v_pk_mul_f32 v[2:3], v[18:19], v[2:3]
	s_nop 0
	v_pk_mul_f32 v[2:3], v[2:3], v[6:7]
	v_lshlrev_b32_e32 v6, 16, v13
	v_mul_f32_e32 v0, 0xbfb8aa3b, v6
	v_exp_f32_e32 v0, v0
	v_and_b32_e32 v7, 0xffff0000, v13
	v_cvt_pk_bf16_f32 v2, v2, v3
	v_add_f32_e32 v0, 1.0, v0
	v_rcp_f32_e32 v12, v0
	v_mul_f32_e32 v0, 0xbfb8aa3b, v7
	v_exp_f32_e32 v0, v0
	s_nop 0
	v_add_f32_e32 v0, 1.0, v0
	v_rcp_f32_e32 v13, v0
	s_nop 0
	v_pk_mul_f32 v[6:7], v[12:13], v[6:7]
	s_nop 0
	v_pk_mul_f32 v[6:7], v[6:7], v[8:9]
	s_nop 0
	v_cvt_pk_bf16_f32 v3, v6, v7
	v_lshlrev_b32_e32 v6, 16, v14
	v_mul_f32_e32 v0, 0xbfb8aa3b, v6
	v_exp_f32_e32 v0, v0
	v_and_b32_e32 v7, 0xffff0000, v14
	v_add_f32_e32 v0, 1.0, v0
	v_rcp_f32_e32 v8, v0
	v_mul_f32_e32 v0, 0xbfb8aa3b, v7
	v_exp_f32_e32 v0, v0
	s_nop 0
	v_add_f32_e32 v0, 1.0, v0
	v_rcp_f32_e32 v9, v0
	s_nop 0
	v_pk_mul_f32 v[6:7], v[8:9], v[6:7]
	s_nop 0
	v_pk_mul_f32 v[4:5], v[6:7], v[4:5]
	v_lshlrev_b32_e32 v6, 16, v15
	v_mul_f32_e32 v0, 0xbfb8aa3b, v6
	v_exp_f32_e32 v0, v0
	v_and_b32_e32 v7, 0xffff0000, v15
	v_cvt_pk_bf16_f32 v4, v4, v5
	v_add_f32_e32 v0, 1.0, v0
	v_rcp_f32_e32 v8, v0
	v_mul_f32_e32 v0, 0xbfb8aa3b, v7
	v_exp_f32_e32 v0, v0
	s_nop 0
	v_add_f32_e32 v0, 1.0, v0
	v_rcp_f32_e32 v9, v0
	s_nop 0
	v_pk_mul_f32 v[6:7], v[8:9], v[6:7]
	s_nop 0
	v_pk_mul_f32 v[6:7], v[6:7], v[16:17]
	s_nop 0
	v_cvt_pk_bf16_f32 v5, v6, v7
	global_store_dwordx4 v[10:11], v[2:5], off offset:2112
	s_cbranch_scc1 .LBB0_516
